# code placement: the six GEMM K-loop heads moved to 8-byte-aligned offsets (one s_nop before four peeled copies)
# speedup vs baseline: 1.0056x; 1.0056x over previous
.LBB0_195:
	v_mov_b32_e32 v127, 0
	s_andn2_b64 vcc, exec, s[80:81]
	v_mov_b32_e32 v126, v127
	v_mov_b32_e32 v125, v127
	v_mov_b32_e32 v124, v127
	v_mov_b32_e32 v123, v127
	v_mov_b32_e32 v122, v127
	v_mov_b32_e32 v121, v127
	v_mov_b32_e32 v120, v127
	v_mov_b32_e32 v111, v127
	v_mov_b32_e32 v110, v127
	v_mov_b32_e32 v109, v127
	v_mov_b32_e32 v108, v127
	v_mov_b32_e32 v107, v127
	v_mov_b32_e32 v106, v127
	v_mov_b32_e32 v105, v127
	v_mov_b32_e32 v104, v127
	v_mov_b32_e32 v95, v127
	v_mov_b32_e32 v94, v127
	v_mov_b32_e32 v93, v127
	v_mov_b32_e32 v92, v127
	v_mov_b32_e32 v91, v127
	v_mov_b32_e32 v90, v127
	v_mov_b32_e32 v89, v127
	v_mov_b32_e32 v88, v127
	v_mov_b32_e32 v79, v127
	v_mov_b32_e32 v78, v127
	v_mov_b32_e32 v77, v127
	v_mov_b32_e32 v76, v127
	v_mov_b32_e32 v75, v127
	v_mov_b32_e32 v74, v127
	v_mov_b32_e32 v73, v127
	v_mov_b32_e32 v72, v127
	v_mov_b32_e32 v119, v127
	v_mov_b32_e32 v118, v127
	v_mov_b32_e32 v117, v127
	v_mov_b32_e32 v116, v127
	v_mov_b32_e32 v115, v127
	v_mov_b32_e32 v114, v127
	v_mov_b32_e32 v113, v127
	v_mov_b32_e32 v112, v127
	v_mov_b32_e32 v103, v127
	v_mov_b32_e32 v102, v127
	v_mov_b32_e32 v101, v127
	v_mov_b32_e32 v100, v127
	v_mov_b32_e32 v99, v127
	v_mov_b32_e32 v98, v127
	v_mov_b32_e32 v97, v127
	v_mov_b32_e32 v96, v127
	v_mov_b32_e32 v87, v127
	v_mov_b32_e32 v86, v127
	v_mov_b32_e32 v85, v127
	v_mov_b32_e32 v84, v127
	v_mov_b32_e32 v83, v127
	v_mov_b32_e32 v82, v127
	v_mov_b32_e32 v81, v127
	v_mov_b32_e32 v80, v127
	v_mov_b32_e32 v71, v127
	v_mov_b32_e32 v70, v127
	v_mov_b32_e32 v69, v127
	v_mov_b32_e32 v68, v127
	v_mov_b32_e32 v67, v127
	v_mov_b32_e32 v66, v127
	v_mov_b32_e32 v65, v127
	v_mov_b32_e32 v64, v127
	v_mov_b32_e32 v63, v127
	v_mov_b32_e32 v62, v127
	v_mov_b32_e32 v61, v127
	v_mov_b32_e32 v60, v127
	v_mov_b32_e32 v59, v127
	v_mov_b32_e32 v58, v127
	v_mov_b32_e32 v57, v127
	v_mov_b32_e32 v56, v127
	v_mov_b32_e32 v47, v127
	v_mov_b32_e32 v46, v127
	v_mov_b32_e32 v45, v127
	v_mov_b32_e32 v44, v127
	v_mov_b32_e32 v43, v127
	v_mov_b32_e32 v42, v127
	v_mov_b32_e32 v41, v127
	v_mov_b32_e32 v40, v127
	v_mov_b32_e32 v31, v127
	v_mov_b32_e32 v30, v127
	v_mov_b32_e32 v29, v127
	v_mov_b32_e32 v28, v127
	v_mov_b32_e32 v27, v127
	v_mov_b32_e32 v26, v127
	v_mov_b32_e32 v25, v127
	v_mov_b32_e32 v24, v127
	v_mov_b32_e32 v15, v127
	v_mov_b32_e32 v14, v127
	v_mov_b32_e32 v13, v127
	v_mov_b32_e32 v12, v127
	v_mov_b32_e32 v11, v127
	v_mov_b32_e32 v10, v127
	v_mov_b32_e32 v9, v127
	v_mov_b32_e32 v8, v127
	v_mov_b32_e32 v55, v127
	v_mov_b32_e32 v54, v127
	v_mov_b32_e32 v53, v127
	v_mov_b32_e32 v52, v127
	v_mov_b32_e32 v51, v127
	v_mov_b32_e32 v50, v127
	v_mov_b32_e32 v49, v127
	v_mov_b32_e32 v48, v127
	v_mov_b32_e32 v39, v127
	v_mov_b32_e32 v38, v127
	v_mov_b32_e32 v37, v127
	v_mov_b32_e32 v36, v127
	v_mov_b32_e32 v35, v127
	v_mov_b32_e32 v34, v127
	v_mov_b32_e32 v33, v127
	v_mov_b32_e32 v32, v127
	v_mov_b32_e32 v23, v127
	v_mov_b32_e32 v22, v127
	v_mov_b32_e32 v21, v127
	v_mov_b32_e32 v20, v127
	v_mov_b32_e32 v19, v127
	v_mov_b32_e32 v18, v127
	v_mov_b32_e32 v17, v127
	v_mov_b32_e32 v16, v127
	v_mov_b32_e32 v7, v127
	v_mov_b32_e32 v6, v127
	v_mov_b32_e32 v5, v127
	v_mov_b32_e32 v4, v127
	v_mov_b32_e32 v3, v127
	v_mov_b32_e32 v2, v127
	v_mov_b32_e32 v1, v127
	v_mov_b32_e32 v0, v127
	s_cbranch_vccnz .LBB0_198
	s_add_u32 s10, s6, 0x100
	s_addc_u32 s40, s7, 0
	s_add_u32 s6, s38, 0x80
	s_addc_u32 s7, s39, 0
	s_mov_b32 s2, 0
	s_nop 0
	s_add_i32 s41, s2, 2
	s_add_u32 s21, s6, 0x80
	s_addc_u32 s3, s7, 0
	s_add_i32 s42, 0, 0x10000
	v_add_u32_e32 v140, s42, v154
	ds_read_b128 v[142:145], v140
	ds_read_b128 v[162:165], v140 offset:1024
	ds_read_b128 v[166:169], v140 offset:2048
	ds_read_b128 v[170:173], v140 offset:3072
	s_cmp_eq_u32 s9, s2
	s_cselect_b32 s2, s68, s21
	s_cselect_b32 s3, s69, s3
	s_cselect_b32 s39, s95, s40
	s_cselect_b32 s38, s94, s10
	v_lshl_add_u64 v[226:227], s[6:7], 0, v[138:139]
	s_add_i32 m0, s79, 0xc000
	ds_read_b128 v[174:177], v155
	ds_read_b128 v[178:181], v155 offset:1024
	ds_read_b128 v[182:185], v155 offset:2048
	ds_read_b128 v[186:189], v155 offset:3072
	ds_read_b128 v[206:209], v155 offset:4096
	ds_read_b128 v[214:217], v155 offset:5120
	ds_read_b128 v[218:221], v155 offset:6144
	ds_read_b128 v[222:225], v155 offset:7168
	global_load_lds_dwordx4 v[226:227], off
	v_lshl_add_u64 v[226:227], s[6:7], 0, v[136:137]
	s_add_i32 m0, s79, 0xe000
	s_nop 0
	global_load_lds_dwordx4 v[226:227], off
	s_waitcnt lgkmcnt(8)
	s_barrier
	s_waitcnt lgkmcnt(0)
	v_mfma_f32_16x16x32_bf16 v[124:127], v[142:145], v[174:177], 0
	v_mfma_f32_16x16x32_bf16 v[120:123], v[166:169], v[174:177], 0
	v_mfma_f32_16x16x32_bf16 v[108:111], v[142:145], v[182:185], 0
	v_mfma_f32_16x16x32_bf16 v[104:107], v[166:169], v[182:185], 0
	v_mfma_f32_16x16x32_bf16 v[92:95], v[142:145], v[206:209], 0
	v_mfma_f32_16x16x32_bf16 v[88:91], v[166:169], v[206:209], 0
	v_mfma_f32_16x16x32_bf16 v[76:79], v[142:145], v[218:221], 0
	v_mfma_f32_16x16x32_bf16 v[72:75], v[166:169], v[218:221], 0
	v_mfma_f32_16x16x32_bf16 v[124:127], v[162:165], v[178:181], v[124:127]
	v_mfma_f32_16x16x32_bf16 v[120:123], v[170:173], v[178:181], v[120:123]
	v_mfma_f32_16x16x32_bf16 v[108:111], v[162:165], v[186:189], v[108:111]
	v_mfma_f32_16x16x32_bf16 v[104:107], v[170:173], v[186:189], v[104:107]
	v_mfma_f32_16x16x32_bf16 v[92:95], v[162:165], v[214:217], v[92:95]
	v_mfma_f32_16x16x32_bf16 v[88:91], v[170:173], v[214:217], v[88:91]
	v_mfma_f32_16x16x32_bf16 v[76:79], v[162:165], v[222:225], v[76:79]
	v_mfma_f32_16x16x32_bf16 v[72:75], v[170:173], v[222:225], v[72:75]
	s_barrier
	s_add_i32 s21, 0, 0x14000
	s_add_i32 s42, s42, s54
	v_add_u32_e32 v140, s21, v154
	v_lshl_add_u64 v[242:243], s[38:39], 0, v[130:131]
	s_mov_b32 m0, s42
	ds_read_b128 v[226:229], v140
	ds_read_b128 v[230:233], v140 offset:1024
	ds_read_b128 v[234:237], v140 offset:2048
	ds_read_b128 v[238:241], v140 offset:3072
	global_load_lds_dwordx4 v[242:243], off
	v_lshl_add_u64 v[244:245], s[38:39], 0, v[128:129]
	s_add_i32 m0, s42, 0x2000
	s_nop 0
	global_load_lds_dwordx4 v[244:245], off
	s_barrier
	s_waitcnt lgkmcnt(0)
	v_mfma_f32_16x16x32_bf16 v[116:119], v[226:229], v[174:177], 0
	v_mfma_f32_16x16x32_bf16 v[112:115], v[234:237], v[174:177], 0
	v_mfma_f32_16x16x32_bf16 v[100:103], v[226:229], v[182:185], 0
	v_mfma_f32_16x16x32_bf16 v[96:99], v[234:237], v[182:185], 0
	v_mfma_f32_16x16x32_bf16 v[84:87], v[226:229], v[206:209], 0
	v_mfma_f32_16x16x32_bf16 v[80:83], v[234:237], v[206:209], 0
	v_mfma_f32_16x16x32_bf16 v[68:71], v[226:229], v[218:221], 0
	v_mfma_f32_16x16x32_bf16 v[64:67], v[234:237], v[218:221], 0
	v_mfma_f32_16x16x32_bf16 v[116:119], v[230:233], v[178:181], v[116:119]
	v_mfma_f32_16x16x32_bf16 v[112:115], v[238:241], v[178:181], v[112:115]
	v_mfma_f32_16x16x32_bf16 v[100:103], v[230:233], v[186:189], v[100:103]
	v_mfma_f32_16x16x32_bf16 v[96:99], v[238:241], v[186:189], v[96:99]
	v_mfma_f32_16x16x32_bf16 v[84:87], v[230:233], v[214:217], v[84:87]
	v_mfma_f32_16x16x32_bf16 v[80:83], v[238:241], v[214:217], v[80:83]
	v_mfma_f32_16x16x32_bf16 v[68:71], v[230:233], v[222:225], v[68:71]
	v_mfma_f32_16x16x32_bf16 v[64:67], v[238:241], v[222:225], v[64:67]
	s_mov_b32 m0, s79
	v_lshl_add_u64 v[246:247], s[2:3], 0, v[130:131]
	s_barrier
	ds_read_b128 v[174:177], v155 offset:16384
	ds_read_b128 v[178:181], v155 offset:17408
	ds_read_b128 v[182:185], v155 offset:18432
	ds_read_b128 v[186:189], v155 offset:19456
	ds_read_b128 v[206:209], v155 offset:20480
	ds_read_b128 v[214:217], v155 offset:21504
	ds_read_b128 v[218:221], v155 offset:22528
	ds_read_b128 v[222:225], v155 offset:23552
	global_load_lds_dwordx4 v[246:247], off
	v_lshl_add_u64 v[248:249], s[2:3], 0, v[128:129]
	s_mov_b32 m0, s34
	s_nop 0
	global_load_lds_dwordx4 v[248:249], off
	s_barrier
	s_waitcnt lgkmcnt(0)
	v_mfma_f32_16x16x32_bf16 v[60:63], v[142:145], v[174:177], 0
	v_mfma_f32_16x16x32_bf16 v[56:59], v[166:169], v[174:177], 0
	v_mfma_f32_16x16x32_bf16 v[44:47], v[142:145], v[182:185], 0
	v_mfma_f32_16x16x32_bf16 v[40:43], v[166:169], v[182:185], 0
	v_mfma_f32_16x16x32_bf16 v[28:31], v[142:145], v[206:209], 0
	v_mfma_f32_16x16x32_bf16 v[24:27], v[166:169], v[206:209], 0
	v_mfma_f32_16x16x32_bf16 v[12:15], v[142:145], v[218:221], 0
	v_mfma_f32_16x16x32_bf16 v[8:11], v[166:169], v[218:221], 0
	v_mfma_f32_16x16x32_bf16 v[60:63], v[162:165], v[178:181], v[60:63]
	v_mfma_f32_16x16x32_bf16 v[56:59], v[170:173], v[178:181], v[56:59]
	v_mfma_f32_16x16x32_bf16 v[44:47], v[162:165], v[186:189], v[44:47]
	v_mfma_f32_16x16x32_bf16 v[40:43], v[170:173], v[186:189], v[40:43]
	v_mfma_f32_16x16x32_bf16 v[28:31], v[162:165], v[214:217], v[28:31]
	v_mfma_f32_16x16x32_bf16 v[24:27], v[170:173], v[214:217], v[24:27]
	v_mfma_f32_16x16x32_bf16 v[12:15], v[162:165], v[222:225], v[12:15]
	v_mfma_f32_16x16x32_bf16 v[8:11], v[170:173], v[222:225], v[8:11]
	s_barrier
	s_add_u32 s38, s38, s88
	s_addc_u32 s39, s39, s89
	s_add_i32 s21, s21, s54
	v_lshl_add_u64 v[250:251], s[38:39], 0, v[130:131]
	s_mov_b32 m0, s21
	v_lshl_add_u64 v[252:253], s[38:39], 0, v[128:129]
	global_load_lds_dwordx4 v[250:251], off
	s_add_i32 m0, s21, 0x2000
	s_nop 0
	global_load_lds_dwordx4 v[252:253], off
	s_waitcnt vmcnt(6)
	s_barrier
	v_mfma_f32_16x16x32_bf16 v[52:55], v[226:229], v[174:177], 0
	v_mfma_f32_16x16x32_bf16 v[48:51], v[234:237], v[174:177], 0
	v_mfma_f32_16x16x32_bf16 v[36:39], v[226:229], v[182:185], 0
	v_mfma_f32_16x16x32_bf16 v[32:35], v[234:237], v[182:185], 0
	v_mfma_f32_16x16x32_bf16 v[20:23], v[226:229], v[206:209], 0
	v_mfma_f32_16x16x32_bf16 v[16:19], v[234:237], v[206:209], 0
	v_mfma_f32_16x16x32_bf16 v[4:7], v[226:229], v[218:221], 0
	v_mfma_f32_16x16x32_bf16 v[0:3], v[234:237], v[218:221], 0
	v_mfma_f32_16x16x32_bf16 v[52:55], v[230:233], v[178:181], v[52:55]
	v_mfma_f32_16x16x32_bf16 v[48:51], v[238:241], v[178:181], v[48:51]
	v_mfma_f32_16x16x32_bf16 v[36:39], v[230:233], v[186:189], v[36:39]
	v_mfma_f32_16x16x32_bf16 v[32:35], v[238:241], v[186:189], v[32:35]
	v_mfma_f32_16x16x32_bf16 v[20:23], v[230:233], v[214:217], v[20:23]
	v_mfma_f32_16x16x32_bf16 v[16:19], v[238:241], v[214:217], v[16:19]
	v_mfma_f32_16x16x32_bf16 v[4:7], v[230:233], v[222:225], v[4:7]
	v_mfma_f32_16x16x32_bf16 v[0:3], v[238:241], v[222:225], v[0:3]
	s_add_i32 s21, 0, 0x18000
	v_add_u32_e32 v140, s21, v154
	s_barrier
	ds_read_b128 v[142:145], v140
	ds_read_b128 v[162:165], v140 offset:1024
	ds_read_b128 v[166:169], v140 offset:2048
	ds_read_b128 v[170:173], v140 offset:3072
	s_add_u32 s2, s2, s88
	s_addc_u32 s3, s3, s89
	s_mov_b32 m0, s35
	v_lshl_add_u64 v[226:227], s[2:3], 0, v[130:131]
	ds_read_b128 v[174:177], v155 offset:32768
	ds_read_b128 v[178:181], v155 offset:33792
	ds_read_b128 v[182:185], v155 offset:34816
	ds_read_b128 v[186:189], v155 offset:35840
	ds_read_b128 v[206:209], v155 offset:36864
	ds_read_b128 v[214:217], v155 offset:37888
	ds_read_b128 v[218:221], v155 offset:38912
	ds_read_b128 v[222:225], v155 offset:39936
	global_load_lds_dwordx4 v[226:227], off
	v_lshl_add_u64 v[226:227], s[2:3], 0, v[128:129]
	s_mov_b32 m0, s44
	s_nop 0
	global_load_lds_dwordx4 v[226:227], off
	s_waitcnt lgkmcnt(8)
	s_barrier
	s_waitcnt lgkmcnt(0)
	v_mfma_f32_16x16x32_bf16 v[124:127], v[142:145], v[174:177], v[124:127]
	v_mfma_f32_16x16x32_bf16 v[120:123], v[166:169], v[174:177], v[120:123]
	v_mfma_f32_16x16x32_bf16 v[108:111], v[142:145], v[182:185], v[108:111]
	v_mfma_f32_16x16x32_bf16 v[104:107], v[166:169], v[182:185], v[104:107]
	v_mfma_f32_16x16x32_bf16 v[92:95], v[142:145], v[206:209], v[92:95]
	v_mfma_f32_16x16x32_bf16 v[88:91], v[166:169], v[206:209], v[88:91]
	v_mfma_f32_16x16x32_bf16 v[76:79], v[142:145], v[218:221], v[76:79]
	v_mfma_f32_16x16x32_bf16 v[72:75], v[166:169], v[218:221], v[72:75]
	v_mfma_f32_16x16x32_bf16 v[124:127], v[162:165], v[178:181], v[124:127]
	v_mfma_f32_16x16x32_bf16 v[120:123], v[170:173], v[178:181], v[120:123]
	v_mfma_f32_16x16x32_bf16 v[108:111], v[162:165], v[186:189], v[108:111]
	v_mfma_f32_16x16x32_bf16 v[104:107], v[170:173], v[186:189], v[104:107]
	v_mfma_f32_16x16x32_bf16 v[92:95], v[162:165], v[214:217], v[92:95]
	v_mfma_f32_16x16x32_bf16 v[88:91], v[170:173], v[214:217], v[88:91]
	v_mfma_f32_16x16x32_bf16 v[76:79], v[162:165], v[222:225], v[76:79]
	v_mfma_f32_16x16x32_bf16 v[72:75], v[170:173], v[222:225], v[72:75]
	s_barrier
	s_add_i32 s2, 0, 0x1c000
	s_add_i32 s3, s21, s54
	v_add_u32_e32 v140, s2, v154
	v_lshl_add_u64 v[242:243], v[242:243], 0, s[50:51]
	s_mov_b32 m0, s3
	ds_read_b128 v[226:229], v140
	ds_read_b128 v[230:233], v140 offset:1024
	ds_read_b128 v[234:237], v140 offset:2048
	ds_read_b128 v[238:241], v140 offset:3072
	global_load_lds_dwordx4 v[242:243], off
	v_lshl_add_u64 v[242:243], v[244:245], 0, s[50:51]
	s_add_i32 m0, s3, 0x2000
	s_nop 0
	global_load_lds_dwordx4 v[242:243], off
	s_barrier
	s_waitcnt lgkmcnt(0)
	v_mfma_f32_16x16x32_bf16 v[116:119], v[226:229], v[174:177], v[116:119]
	v_mfma_f32_16x16x32_bf16 v[112:115], v[234:237], v[174:177], v[112:115]
	v_mfma_f32_16x16x32_bf16 v[100:103], v[226:229], v[182:185], v[100:103]
	v_mfma_f32_16x16x32_bf16 v[96:99], v[234:237], v[182:185], v[96:99]
	v_mfma_f32_16x16x32_bf16 v[84:87], v[226:229], v[206:209], v[84:87]
	v_mfma_f32_16x16x32_bf16 v[80:83], v[234:237], v[206:209], v[80:83]
	v_mfma_f32_16x16x32_bf16 v[68:71], v[226:229], v[218:221], v[68:71]
	v_mfma_f32_16x16x32_bf16 v[64:67], v[234:237], v[218:221], v[64:67]
	v_mfma_f32_16x16x32_bf16 v[116:119], v[230:233], v[178:181], v[116:119]
	v_mfma_f32_16x16x32_bf16 v[112:115], v[238:241], v[178:181], v[112:115]
	v_mfma_f32_16x16x32_bf16 v[100:103], v[230:233], v[186:189], v[100:103]
	v_mfma_f32_16x16x32_bf16 v[96:99], v[238:241], v[186:189], v[96:99]
	v_mfma_f32_16x16x32_bf16 v[84:87], v[230:233], v[214:217], v[84:87]
	v_mfma_f32_16x16x32_bf16 v[80:83], v[238:241], v[214:217], v[80:83]
	v_mfma_f32_16x16x32_bf16 v[68:71], v[230:233], v[222:225], v[68:71]
	v_mfma_f32_16x16x32_bf16 v[64:67], v[238:241], v[222:225], v[64:67]
	s_mov_b32 m0, s82
	v_lshl_add_u64 v[242:243], v[246:247], 0, s[50:51]
	s_barrier
	ds_read_b128 v[174:177], v155 offset:49152
	ds_read_b128 v[178:181], v155 offset:50176
	ds_read_b128 v[182:185], v155 offset:51200
	ds_read_b128 v[186:189], v155 offset:52224
	ds_read_b128 v[206:209], v155 offset:53248
	ds_read_b128 v[214:217], v155 offset:54272
	ds_read_b128 v[218:221], v155 offset:55296
	ds_read_b128 v[222:225], v155 offset:56320
	global_load_lds_dwordx4 v[242:243], off
	v_lshl_add_u64 v[242:243], v[248:249], 0, s[50:51]
	s_mov_b32 m0, s83
	s_nop 0
	global_load_lds_dwordx4 v[242:243], off
	s_barrier
	s_waitcnt lgkmcnt(0)
	v_mfma_f32_16x16x32_bf16 v[60:63], v[142:145], v[174:177], v[60:63]
	v_mfma_f32_16x16x32_bf16 v[56:59], v[166:169], v[174:177], v[56:59]
	v_mfma_f32_16x16x32_bf16 v[44:47], v[142:145], v[182:185], v[44:47]
	v_mfma_f32_16x16x32_bf16 v[40:43], v[166:169], v[182:185], v[40:43]
	v_mfma_f32_16x16x32_bf16 v[28:31], v[142:145], v[206:209], v[28:31]
	v_mfma_f32_16x16x32_bf16 v[24:27], v[166:169], v[206:209], v[24:27]
	v_mfma_f32_16x16x32_bf16 v[12:15], v[142:145], v[218:221], v[12:15]
	v_mfma_f32_16x16x32_bf16 v[8:11], v[166:169], v[218:221], v[8:11]
	v_mfma_f32_16x16x32_bf16 v[60:63], v[162:165], v[178:181], v[60:63]
	v_mfma_f32_16x16x32_bf16 v[56:59], v[170:173], v[178:181], v[56:59]
	v_mfma_f32_16x16x32_bf16 v[44:47], v[162:165], v[186:189], v[44:47]
	v_mfma_f32_16x16x32_bf16 v[40:43], v[170:173], v[186:189], v[40:43]
	v_mfma_f32_16x16x32_bf16 v[28:31], v[162:165], v[214:217], v[28:31]
	v_mfma_f32_16x16x32_bf16 v[24:27], v[170:173], v[214:217], v[24:27]
	v_mfma_f32_16x16x32_bf16 v[12:15], v[162:165], v[222:225], v[12:15]
	v_mfma_f32_16x16x32_bf16 v[8:11], v[170:173], v[222:225], v[8:11]
	s_barrier
	s_add_i32 s2, s2, s54
	v_lshl_add_u64 v[142:143], v[250:251], 0, s[50:51]
	s_mov_b32 m0, s2
	s_nop 0
	global_load_lds_dwordx4 v[142:143], off
	v_lshl_add_u64 v[142:143], v[252:253], 0, s[50:51]
	s_add_i32 m0, s2, 0x2000
	s_nop 0
	global_load_lds_dwordx4 v[142:143], off
	s_waitcnt vmcnt(6)
	s_barrier
	v_mfma_f32_16x16x32_bf16 v[52:55], v[226:229], v[174:177], v[52:55]
	v_mfma_f32_16x16x32_bf16 v[48:51], v[234:237], v[174:177], v[48:51]
	v_mfma_f32_16x16x32_bf16 v[36:39], v[226:229], v[182:185], v[36:39]
	v_mfma_f32_16x16x32_bf16 v[32:35], v[234:237], v[182:185], v[32:35]
	v_mfma_f32_16x16x32_bf16 v[20:23], v[226:229], v[206:209], v[20:23]
	v_mfma_f32_16x16x32_bf16 v[16:19], v[234:237], v[206:209], v[16:19]
	v_mfma_f32_16x16x32_bf16 v[4:7], v[226:229], v[218:221], v[4:7]
	v_mfma_f32_16x16x32_bf16 v[0:3], v[234:237], v[218:221], v[0:3]
	v_mfma_f32_16x16x32_bf16 v[52:55], v[230:233], v[178:181], v[52:55]
	v_mfma_f32_16x16x32_bf16 v[48:51], v[238:241], v[178:181], v[48:51]
	v_mfma_f32_16x16x32_bf16 v[36:39], v[230:233], v[186:189], v[36:39]
	v_mfma_f32_16x16x32_bf16 v[32:35], v[238:241], v[186:189], v[32:35]
	v_mfma_f32_16x16x32_bf16 v[20:23], v[230:233], v[214:217], v[20:23]
	v_mfma_f32_16x16x32_bf16 v[16:19], v[238:241], v[214:217], v[16:19]
	v_mfma_f32_16x16x32_bf16 v[4:7], v[230:233], v[222:225], v[4:7]
	v_mfma_f32_16x16x32_bf16 v[0:3], v[238:241], v[222:225], v[0:3]
	s_add_u32 s10, s10, 0x100
	s_addc_u32 s40, s40, 0
	s_add_u32 s6, s6, 0x100
	s_addc_u32 s7, s7, 0
	s_cmp_ge_i32 s41, s66
	s_mov_b32 s2, s41
	s_barrier
	s_cbranch_scc1 .Lpost_197

.LBB0_270:
	v_lshl_add_u64 v[0:1], s[40:41], 0, v[156:157]
	v_mov_b32_e32 v129, v157
	v_lshl_add_u64 v[4:5], s[2:3], 0, v[156:157]
	v_lshl_add_u64 v[6:7], s[2:3], 0, v[128:129]
	s_lshl_b32 s2, s19, 5
	s_add_i32 m0, s25, 0x18000
	v_lshl_add_u64 v[0:1], v[0:1], 0, s[50:51]
	s_and_b32 s19, s2, 0x60
	s_waitcnt vmcnt(4)
	s_barrier
	global_load_lds_dwordx4 v[0:1], off
	s_add_i32 m0, s25, 0x1a000
	v_lshl_add_u64 v[2:3], s[40:41], 0, v[128:129]
	s_add_u32 s2, s26, 0x1a4a4080
	v_lshl_add_u64 v[0:1], v[2:3], 0, s[50:51]
	s_addc_u32 s3, s27, 0
	s_add_i32 s45, s25, 0x8000
	global_load_lds_dwordx4 v[0:1], off
	v_lshl_add_u64 v[0:1], s[2:3], 0, v[156:157]
	s_mov_b32 m0, s45
	s_add_i32 s48, s25, 0xa000
	global_load_lds_dwordx4 v[0:1], off
	v_lshl_add_u64 v[0:1], s[2:3], 0, v[128:129]
	s_mov_b32 m0, s48
	v_mov_b32_e32 v127, 0
	global_load_lds_dwordx4 v[0:1], off
	s_add_i32 m0, s25, 0x1c000
	v_lshl_add_u64 v[0:1], v[4:5], 0, s[50:51]
	global_load_lds_dwordx4 v[0:1], off
	v_lshl_add_u64 v[0:1], v[6:7], 0, s[50:51]
	s_add_i32 m0, s25, 0x1e000
	v_lshl_or_b32 v134, s42, 6, v149
	global_load_lds_dwordx4 v[0:1], off
	s_waitcnt vmcnt(6)
	s_cmp_lt_i32 s6, 64
	v_mov_b32_e32 v126, v127
	v_mov_b32_e32 v125, v127
	v_mov_b32_e32 v124, v127
	v_mov_b32_e32 v123, v127
	v_mov_b32_e32 v122, v127
	v_mov_b32_e32 v121, v127
	v_mov_b32_e32 v120, v127
	v_mov_b32_e32 v111, v127
	v_mov_b32_e32 v110, v127
	v_mov_b32_e32 v109, v127
	v_mov_b32_e32 v108, v127
	v_mov_b32_e32 v107, v127
	v_mov_b32_e32 v106, v127
	v_mov_b32_e32 v105, v127
	v_mov_b32_e32 v104, v127
	v_mov_b32_e32 v95, v127
	v_mov_b32_e32 v94, v127
	v_mov_b32_e32 v93, v127
	v_mov_b32_e32 v92, v127
	v_mov_b32_e32 v91, v127
	v_mov_b32_e32 v90, v127
	v_mov_b32_e32 v89, v127
	v_mov_b32_e32 v88, v127
	v_mov_b32_e32 v79, v127
	v_mov_b32_e32 v78, v127
	v_mov_b32_e32 v77, v127
	v_mov_b32_e32 v76, v127
	v_mov_b32_e32 v75, v127
	v_mov_b32_e32 v74, v127
	v_mov_b32_e32 v73, v127
	v_mov_b32_e32 v72, v127
	v_mov_b32_e32 v119, v127
	v_mov_b32_e32 v118, v127
	v_mov_b32_e32 v117, v127
	v_mov_b32_e32 v116, v127
	v_mov_b32_e32 v115, v127
	v_mov_b32_e32 v114, v127
	v_mov_b32_e32 v113, v127
	v_mov_b32_e32 v112, v127
	v_mov_b32_e32 v103, v127
	v_mov_b32_e32 v102, v127
	v_mov_b32_e32 v101, v127
	v_mov_b32_e32 v100, v127
	v_mov_b32_e32 v99, v127
	v_mov_b32_e32 v98, v127
	v_mov_b32_e32 v97, v127
	v_mov_b32_e32 v96, v127
	v_mov_b32_e32 v87, v127
	v_mov_b32_e32 v86, v127
	v_mov_b32_e32 v85, v127
	v_mov_b32_e32 v84, v127
	v_mov_b32_e32 v83, v127
	v_mov_b32_e32 v82, v127
	v_mov_b32_e32 v81, v127
	v_mov_b32_e32 v80, v127
	v_mov_b32_e32 v71, v127
	v_mov_b32_e32 v70, v127
	v_mov_b32_e32 v69, v127
	v_mov_b32_e32 v68, v127
	v_mov_b32_e32 v67, v127
	v_mov_b32_e32 v66, v127
	v_mov_b32_e32 v65, v127
	v_mov_b32_e32 v64, v127
	v_mov_b32_e32 v63, v127
	v_mov_b32_e32 v62, v127
	v_mov_b32_e32 v61, v127
	v_mov_b32_e32 v60, v127
	v_mov_b32_e32 v59, v127
	v_mov_b32_e32 v58, v127
	v_mov_b32_e32 v57, v127
	v_mov_b32_e32 v56, v127
	v_mov_b32_e32 v47, v127
	v_mov_b32_e32 v46, v127
	v_mov_b32_e32 v45, v127
	v_mov_b32_e32 v44, v127
	v_mov_b32_e32 v43, v127
	v_mov_b32_e32 v42, v127
	v_mov_b32_e32 v41, v127
	v_mov_b32_e32 v40, v127
	v_mov_b32_e32 v31, v127
	v_mov_b32_e32 v30, v127
	v_mov_b32_e32 v29, v127
	v_mov_b32_e32 v28, v127
	v_mov_b32_e32 v27, v127
	v_mov_b32_e32 v26, v127
	v_mov_b32_e32 v25, v127
	v_mov_b32_e32 v24, v127
	v_mov_b32_e32 v15, v127
	v_mov_b32_e32 v14, v127
	v_mov_b32_e32 v13, v127
	v_mov_b32_e32 v12, v127
	v_mov_b32_e32 v11, v127
	v_mov_b32_e32 v10, v127
	v_mov_b32_e32 v9, v127
	v_mov_b32_e32 v8, v127
	v_mov_b32_e32 v55, v127
	v_mov_b32_e32 v54, v127
	v_mov_b32_e32 v53, v127
	v_mov_b32_e32 v52, v127
	v_mov_b32_e32 v51, v127
	v_mov_b32_e32 v50, v127
	v_mov_b32_e32 v49, v127
	v_mov_b32_e32 v48, v127
	v_mov_b32_e32 v39, v127
	v_mov_b32_e32 v38, v127
	v_mov_b32_e32 v37, v127
	v_mov_b32_e32 v36, v127
	v_mov_b32_e32 v35, v127
	v_mov_b32_e32 v34, v127
	v_mov_b32_e32 v33, v127
	v_mov_b32_e32 v32, v127
	v_mov_b32_e32 v23, v127
	v_mov_b32_e32 v22, v127
	v_mov_b32_e32 v21, v127
	v_mov_b32_e32 v20, v127
	v_mov_b32_e32 v19, v127
	v_mov_b32_e32 v18, v127
	v_mov_b32_e32 v17, v127
	v_mov_b32_e32 v16, v127
	v_mov_b32_e32 v7, v127
	v_mov_b32_e32 v6, v127
	v_mov_b32_e32 v5, v127
	v_mov_b32_e32 v4, v127
	v_mov_b32_e32 v3, v127
	v_mov_b32_e32 v2, v127
	v_mov_b32_e32 v1, v127
	v_mov_b32_e32 v0, v127
	s_barrier
	s_cbranch_scc1 .LBB0_273
	s_lshr_b32 s2, s7, 26
	s_add_i32 s2, s6, s2
	s_ashr_i32 s49, s2, 6
	v_lshlrev_b32_e32 v0, 6, v134
	s_movk_i32 s2, 0x3c0
	v_lshlrev_b32_e32 v1, 2, v134
	s_add_i32 s53, s49, -2
	v_and_or_b32 v0, v0, s2, v147
	s_lshl_b32 s2, s42, 13
	v_and_b32_e32 v1, 32, v1
	v_bitop3_b32 v2, v0, s2, v1 bitop3:0xde
	s_add_u32 s2, s26, s36
	v_add_u32_e32 v0, v132, v133
	s_addc_u32 s3, s27, s37
	v_add_lshl_u32 v0, v0, v146, 1
	v_mov_b32_e32 v1, v157
	v_lshl_add_u64 v[132:133], s[2:3], 0, v[0:1]
	v_lshl_or_b32 v135, s19, 7, v148
	v_lshl_add_u64 v[130:131], s[2:3], 0, v[128:129]
	s_mov_b32 s2, 0
	s_mov_b64 s[6:7], 0x1a4a4080
	v_add_u32_e32 v136, 0, v2
	s_nop 0
	s_add_i32 s54, s2, 2
	s_add_u32 s3, s6, 0xe5b5c080
	s_addc_u32 s21, s7, -1
	s_cmp_lg_u32 s53, s2
	s_cselect_b32 s42, s3, 0
	s_cselect_b32 s21, s21, 0
	s_add_u32 s2, s38, s42
	s_addc_u32 s3, s39, s21
	s_add_i32 s55, 0, 0x10000
	v_add_u32_e32 v137, s55, v135
	ds_read_b128 v[142:145], v137
	ds_read_b128 v[146:149], v137 offset:1024
	ds_read_b128 v[150:153], v137 offset:2048
	ds_read_b128 v[162:165], v137 offset:3072
	s_add_u32 s42, s40, s42
	s_addc_u32 s43, s41, s21
	v_lshl_add_u64 v[138:139], v[132:133], 0, s[6:7]
	s_add_i32 m0, s25, 0xc000
	ds_read_b128 v[166:169], v136
	ds_read_b128 v[170:173], v136 offset:1024
	ds_read_b128 v[174:177], v136 offset:2048
	ds_read_b128 v[178:181], v136 offset:3072
	ds_read_b128 v[182:185], v136 offset:4096
	ds_read_b128 v[186:189], v136 offset:5120
	ds_read_b128 v[206:209], v136 offset:6144
	ds_read_b128 v[214:217], v136 offset:7168
	global_load_lds_dwordx4 v[138:139], off
	v_lshl_add_u64 v[138:139], v[130:131], 0, s[6:7]
	s_add_i32 m0, s25, 0xe000
	s_nop 0
	global_load_lds_dwordx4 v[138:139], off
	s_waitcnt lgkmcnt(8)
	s_barrier
	s_waitcnt lgkmcnt(0)
	v_mfma_f32_16x16x32_bf16 v[124:127], v[142:145], v[166:169], 0
	v_mfma_f32_16x16x32_bf16 v[120:123], v[150:153], v[166:169], 0
	v_mfma_f32_16x16x32_bf16 v[108:111], v[142:145], v[174:177], 0
	v_mfma_f32_16x16x32_bf16 v[104:107], v[150:153], v[174:177], 0
	v_mfma_f32_16x16x32_bf16 v[92:95], v[142:145], v[182:185], 0
	v_mfma_f32_16x16x32_bf16 v[88:91], v[150:153], v[182:185], 0
	v_mfma_f32_16x16x32_bf16 v[76:79], v[142:145], v[206:209], 0
	v_mfma_f32_16x16x32_bf16 v[72:75], v[150:153], v[206:209], 0
	v_mfma_f32_16x16x32_bf16 v[124:127], v[146:149], v[170:173], v[124:127]
	v_mfma_f32_16x16x32_bf16 v[120:123], v[162:165], v[170:173], v[120:123]
	v_mfma_f32_16x16x32_bf16 v[108:111], v[146:149], v[178:181], v[108:111]
	v_mfma_f32_16x16x32_bf16 v[104:107], v[162:165], v[178:181], v[104:107]
	v_mfma_f32_16x16x32_bf16 v[92:95], v[146:149], v[186:189], v[92:95]
	v_mfma_f32_16x16x32_bf16 v[88:91], v[162:165], v[186:189], v[88:91]
	v_mfma_f32_16x16x32_bf16 v[76:79], v[146:149], v[214:217], v[76:79]
	v_mfma_f32_16x16x32_bf16 v[72:75], v[162:165], v[214:217], v[72:75]
	s_barrier
	s_add_i32 s21, 0, 0x14000
	s_add_i32 s55, s55, s24
	v_add_u32_e32 v137, s21, v135
	v_lshl_add_u64 v[138:139], s[42:43], 0, v[156:157]
	s_mov_b32 m0, s55
	ds_read_b128 v[218:221], v137
	ds_read_b128 v[222:225], v137 offset:1024
	ds_read_b128 v[226:229], v137 offset:2048
	ds_read_b128 v[230:233], v137 offset:3072
	global_load_lds_dwordx4 v[138:139], off
	v_lshl_add_u64 v[154:155], s[42:43], 0, v[128:129]
	s_add_i32 m0, s55, 0x2000
	s_nop 0
	global_load_lds_dwordx4 v[154:155], off
	s_barrier
	s_waitcnt lgkmcnt(0)
	v_mfma_f32_16x16x32_bf16 v[116:119], v[218:221], v[166:169], 0
	v_mfma_f32_16x16x32_bf16 v[112:115], v[226:229], v[166:169], 0
	v_mfma_f32_16x16x32_bf16 v[100:103], v[218:221], v[174:177], 0
	v_mfma_f32_16x16x32_bf16 v[96:99], v[226:229], v[174:177], 0
	v_mfma_f32_16x16x32_bf16 v[84:87], v[218:221], v[182:185], 0
	v_mfma_f32_16x16x32_bf16 v[80:83], v[226:229], v[182:185], 0
	v_mfma_f32_16x16x32_bf16 v[68:71], v[218:221], v[206:209], 0
	v_mfma_f32_16x16x32_bf16 v[64:67], v[226:229], v[206:209], 0
	v_mfma_f32_16x16x32_bf16 v[116:119], v[222:225], v[170:173], v[116:119]
	v_mfma_f32_16x16x32_bf16 v[112:115], v[230:233], v[170:173], v[112:115]
	v_mfma_f32_16x16x32_bf16 v[100:103], v[222:225], v[178:181], v[100:103]
	v_mfma_f32_16x16x32_bf16 v[96:99], v[230:233], v[178:181], v[96:99]
	v_mfma_f32_16x16x32_bf16 v[84:87], v[222:225], v[186:189], v[84:87]
	v_mfma_f32_16x16x32_bf16 v[80:83], v[230:233], v[186:189], v[80:83]
	v_mfma_f32_16x16x32_bf16 v[68:71], v[222:225], v[214:217], v[68:71]
	v_mfma_f32_16x16x32_bf16 v[64:67], v[230:233], v[214:217], v[64:67]
	s_mov_b32 m0, s25
	v_lshl_add_u64 v[234:235], s[2:3], 0, v[156:157]
	s_barrier
	ds_read_b128 v[166:169], v136 offset:16384
	ds_read_b128 v[170:173], v136 offset:17408
	ds_read_b128 v[174:177], v136 offset:18432
	ds_read_b128 v[178:181], v136 offset:19456
	ds_read_b128 v[182:185], v136 offset:20480
	ds_read_b128 v[186:189], v136 offset:21504
	ds_read_b128 v[206:209], v136 offset:22528
	ds_read_b128 v[214:217], v136 offset:23552
	global_load_lds_dwordx4 v[234:235], off
	v_lshl_add_u64 v[236:237], s[2:3], 0, v[128:129]
	s_mov_b32 m0, s34
	s_nop 0
	global_load_lds_dwordx4 v[236:237], off
	s_barrier
	s_waitcnt lgkmcnt(0)
	v_mfma_f32_16x16x32_bf16 v[60:63], v[142:145], v[166:169], 0
	v_mfma_f32_16x16x32_bf16 v[56:59], v[150:153], v[166:169], 0
	v_mfma_f32_16x16x32_bf16 v[44:47], v[142:145], v[174:177], 0
	v_mfma_f32_16x16x32_bf16 v[40:43], v[150:153], v[174:177], 0
	v_mfma_f32_16x16x32_bf16 v[28:31], v[142:145], v[182:185], 0
	v_mfma_f32_16x16x32_bf16 v[24:27], v[150:153], v[182:185], 0
	v_mfma_f32_16x16x32_bf16 v[12:15], v[142:145], v[206:209], 0
	v_mfma_f32_16x16x32_bf16 v[8:11], v[150:153], v[206:209], 0
	v_mfma_f32_16x16x32_bf16 v[60:63], v[146:149], v[170:173], v[60:63]
	v_mfma_f32_16x16x32_bf16 v[56:59], v[162:165], v[170:173], v[56:59]
	v_mfma_f32_16x16x32_bf16 v[44:47], v[146:149], v[178:181], v[44:47]
	v_mfma_f32_16x16x32_bf16 v[40:43], v[162:165], v[178:181], v[40:43]
	v_mfma_f32_16x16x32_bf16 v[28:31], v[146:149], v[186:189], v[28:31]
	v_mfma_f32_16x16x32_bf16 v[24:27], v[162:165], v[186:189], v[24:27]
	v_mfma_f32_16x16x32_bf16 v[12:15], v[146:149], v[214:217], v[12:15]
	v_mfma_f32_16x16x32_bf16 v[8:11], v[162:165], v[214:217], v[8:11]
	s_barrier
	s_add_u32 s42, s42, s36
	s_addc_u32 s43, s43, s37
	s_add_i32 s21, s21, s24
	v_lshl_add_u64 v[238:239], s[42:43], 0, v[156:157]
	s_mov_b32 m0, s21
	v_lshl_add_u64 v[240:241], s[42:43], 0, v[128:129]
	global_load_lds_dwordx4 v[238:239], off
	s_add_i32 m0, s21, 0x2000
	s_nop 0
	global_load_lds_dwordx4 v[240:241], off
	s_waitcnt vmcnt(6)
	s_barrier
	v_mfma_f32_16x16x32_bf16 v[52:55], v[218:221], v[166:169], 0
	v_mfma_f32_16x16x32_bf16 v[48:51], v[226:229], v[166:169], 0
	v_mfma_f32_16x16x32_bf16 v[36:39], v[218:221], v[174:177], 0
	v_mfma_f32_16x16x32_bf16 v[32:35], v[226:229], v[174:177], 0
	v_mfma_f32_16x16x32_bf16 v[20:23], v[218:221], v[182:185], 0
	v_mfma_f32_16x16x32_bf16 v[16:19], v[226:229], v[182:185], 0
	v_mfma_f32_16x16x32_bf16 v[4:7], v[218:221], v[206:209], 0
	v_mfma_f32_16x16x32_bf16 v[0:3], v[226:229], v[206:209], 0
	v_mfma_f32_16x16x32_bf16 v[52:55], v[222:225], v[170:173], v[52:55]
	v_mfma_f32_16x16x32_bf16 v[48:51], v[230:233], v[170:173], v[48:51]
	v_mfma_f32_16x16x32_bf16 v[36:39], v[222:225], v[178:181], v[36:39]
	v_mfma_f32_16x16x32_bf16 v[32:35], v[230:233], v[178:181], v[32:35]
	v_mfma_f32_16x16x32_bf16 v[20:23], v[222:225], v[186:189], v[20:23]
	v_mfma_f32_16x16x32_bf16 v[16:19], v[230:233], v[186:189], v[16:19]
	v_mfma_f32_16x16x32_bf16 v[4:7], v[222:225], v[214:217], v[4:7]
	v_mfma_f32_16x16x32_bf16 v[0:3], v[230:233], v[214:217], v[0:3]
	s_add_i32 s21, 0, 0x18000
	v_add_u32_e32 v137, s21, v135
	s_barrier
	ds_read_b128 v[142:145], v137
	ds_read_b128 v[146:149], v137 offset:1024
	ds_read_b128 v[150:153], v137 offset:2048
	ds_read_b128 v[162:165], v137 offset:3072
	s_add_u32 s2, s2, s36
	s_addc_u32 s3, s3, s37
	s_mov_b32 m0, s35
	v_lshl_add_u64 v[218:219], s[2:3], 0, v[156:157]
	ds_read_b128 v[166:169], v136 offset:32768
	ds_read_b128 v[170:173], v136 offset:33792
	ds_read_b128 v[174:177], v136 offset:34816
	ds_read_b128 v[178:181], v136 offset:35840
	ds_read_b128 v[182:185], v136 offset:36864
	ds_read_b128 v[186:189], v136 offset:37888
	ds_read_b128 v[206:209], v136 offset:38912
	ds_read_b128 v[214:217], v136 offset:39936
	global_load_lds_dwordx4 v[218:219], off
	v_lshl_add_u64 v[218:219], s[2:3], 0, v[128:129]
	s_mov_b32 m0, s44
	s_nop 0
	global_load_lds_dwordx4 v[218:219], off
	s_waitcnt lgkmcnt(8)
	s_barrier
	s_waitcnt lgkmcnt(0)
	v_mfma_f32_16x16x32_bf16 v[124:127], v[142:145], v[166:169], v[124:127]
	v_mfma_f32_16x16x32_bf16 v[120:123], v[150:153], v[166:169], v[120:123]
	v_mfma_f32_16x16x32_bf16 v[108:111], v[142:145], v[174:177], v[108:111]
	v_mfma_f32_16x16x32_bf16 v[104:107], v[150:153], v[174:177], v[104:107]
	v_mfma_f32_16x16x32_bf16 v[92:95], v[142:145], v[182:185], v[92:95]
	v_mfma_f32_16x16x32_bf16 v[88:91], v[150:153], v[182:185], v[88:91]
	v_mfma_f32_16x16x32_bf16 v[76:79], v[142:145], v[206:209], v[76:79]
	v_mfma_f32_16x16x32_bf16 v[72:75], v[150:153], v[206:209], v[72:75]
	v_mfma_f32_16x16x32_bf16 v[124:127], v[146:149], v[170:173], v[124:127]
	v_mfma_f32_16x16x32_bf16 v[120:123], v[162:165], v[170:173], v[120:123]
	v_mfma_f32_16x16x32_bf16 v[108:111], v[146:149], v[178:181], v[108:111]
	v_mfma_f32_16x16x32_bf16 v[104:107], v[162:165], v[178:181], v[104:107]
	v_mfma_f32_16x16x32_bf16 v[92:95], v[146:149], v[186:189], v[92:95]
	v_mfma_f32_16x16x32_bf16 v[88:91], v[162:165], v[186:189], v[88:91]
	v_mfma_f32_16x16x32_bf16 v[76:79], v[146:149], v[214:217], v[76:79]
	v_mfma_f32_16x16x32_bf16 v[72:75], v[162:165], v[214:217], v[72:75]
	s_barrier
	s_add_i32 s2, 0, 0x1c000
	s_add_i32 s3, s21, s24
	v_add_u32_e32 v137, s2, v135
	v_lshl_add_u64 v[138:139], v[138:139], 0, s[50:51]
	s_mov_b32 m0, s3
	ds_read_b128 v[218:221], v137
	ds_read_b128 v[222:225], v137 offset:1024
	ds_read_b128 v[226:229], v137 offset:2048
	ds_read_b128 v[230:233], v137 offset:3072
	global_load_lds_dwordx4 v[138:139], off
	v_lshl_add_u64 v[138:139], v[154:155], 0, s[50:51]
	s_add_i32 m0, s3, 0x2000
	s_nop 0
	global_load_lds_dwordx4 v[138:139], off
	s_barrier
	s_waitcnt lgkmcnt(0)
	v_mfma_f32_16x16x32_bf16 v[116:119], v[218:221], v[166:169], v[116:119]
	v_mfma_f32_16x16x32_bf16 v[112:115], v[226:229], v[166:169], v[112:115]
	v_mfma_f32_16x16x32_bf16 v[100:103], v[218:221], v[174:177], v[100:103]
	v_mfma_f32_16x16x32_bf16 v[96:99], v[226:229], v[174:177], v[96:99]
	v_mfma_f32_16x16x32_bf16 v[84:87], v[218:221], v[182:185], v[84:87]
	v_mfma_f32_16x16x32_bf16 v[80:83], v[226:229], v[182:185], v[80:83]
	v_mfma_f32_16x16x32_bf16 v[68:71], v[218:221], v[206:209], v[68:71]
	v_mfma_f32_16x16x32_bf16 v[64:67], v[226:229], v[206:209], v[64:67]
	v_mfma_f32_16x16x32_bf16 v[116:119], v[222:225], v[170:173], v[116:119]
	v_mfma_f32_16x16x32_bf16 v[112:115], v[230:233], v[170:173], v[112:115]
	v_mfma_f32_16x16x32_bf16 v[100:103], v[222:225], v[178:181], v[100:103]
	v_mfma_f32_16x16x32_bf16 v[96:99], v[230:233], v[178:181], v[96:99]
	v_mfma_f32_16x16x32_bf16 v[84:87], v[222:225], v[186:189], v[84:87]
	v_mfma_f32_16x16x32_bf16 v[80:83], v[230:233], v[186:189], v[80:83]
	v_mfma_f32_16x16x32_bf16 v[68:71], v[222:225], v[214:217], v[68:71]
	v_mfma_f32_16x16x32_bf16 v[64:67], v[230:233], v[214:217], v[64:67]
	s_mov_b32 m0, s45
	v_lshl_add_u64 v[138:139], v[234:235], 0, s[50:51]
	s_barrier
	ds_read_b128 v[166:169], v136 offset:49152
	ds_read_b128 v[170:173], v136 offset:50176
	ds_read_b128 v[174:177], v136 offset:51200
	ds_read_b128 v[178:181], v136 offset:52224
	ds_read_b128 v[182:185], v136 offset:53248
	ds_read_b128 v[186:189], v136 offset:54272
	ds_read_b128 v[206:209], v136 offset:55296
	ds_read_b128 v[214:217], v136 offset:56320
	global_load_lds_dwordx4 v[138:139], off
	v_lshl_add_u64 v[138:139], v[236:237], 0, s[50:51]
	s_mov_b32 m0, s48
	s_nop 0
	global_load_lds_dwordx4 v[138:139], off
	s_barrier
	s_waitcnt lgkmcnt(0)
	v_mfma_f32_16x16x32_bf16 v[60:63], v[142:145], v[166:169], v[60:63]
	v_mfma_f32_16x16x32_bf16 v[56:59], v[150:153], v[166:169], v[56:59]
	v_mfma_f32_16x16x32_bf16 v[44:47], v[142:145], v[174:177], v[44:47]
	v_mfma_f32_16x16x32_bf16 v[40:43], v[150:153], v[174:177], v[40:43]
	v_mfma_f32_16x16x32_bf16 v[28:31], v[142:145], v[182:185], v[28:31]
	v_mfma_f32_16x16x32_bf16 v[24:27], v[150:153], v[182:185], v[24:27]
	v_mfma_f32_16x16x32_bf16 v[12:15], v[142:145], v[206:209], v[12:15]
	v_mfma_f32_16x16x32_bf16 v[8:11], v[150:153], v[206:209], v[8:11]
	v_mfma_f32_16x16x32_bf16 v[60:63], v[146:149], v[170:173], v[60:63]
	v_mfma_f32_16x16x32_bf16 v[56:59], v[162:165], v[170:173], v[56:59]
	v_mfma_f32_16x16x32_bf16 v[44:47], v[146:149], v[178:181], v[44:47]
	v_mfma_f32_16x16x32_bf16 v[40:43], v[162:165], v[178:181], v[40:43]
	v_mfma_f32_16x16x32_bf16 v[28:31], v[146:149], v[186:189], v[28:31]
	v_mfma_f32_16x16x32_bf16 v[24:27], v[162:165], v[186:189], v[24:27]
	v_mfma_f32_16x16x32_bf16 v[12:15], v[146:149], v[214:217], v[12:15]
	v_mfma_f32_16x16x32_bf16 v[8:11], v[162:165], v[214:217], v[8:11]
	s_barrier
	s_add_i32 s2, s2, s24
	v_lshl_add_u64 v[138:139], v[238:239], 0, s[50:51]
	s_mov_b32 m0, s2
	s_nop 0
	global_load_lds_dwordx4 v[138:139], off
	v_lshl_add_u64 v[138:139], v[240:241], 0, s[50:51]
	s_add_i32 m0, s2, 0x2000
	s_nop 0
	global_load_lds_dwordx4 v[138:139], off
	s_waitcnt vmcnt(6)
	s_barrier
	v_mfma_f32_16x16x32_bf16 v[52:55], v[218:221], v[166:169], v[52:55]
	v_mfma_f32_16x16x32_bf16 v[48:51], v[226:229], v[166:169], v[48:51]
	v_mfma_f32_16x16x32_bf16 v[36:39], v[218:221], v[174:177], v[36:39]
	v_mfma_f32_16x16x32_bf16 v[32:35], v[226:229], v[174:177], v[32:35]
	v_mfma_f32_16x16x32_bf16 v[20:23], v[218:221], v[182:185], v[20:23]
	v_mfma_f32_16x16x32_bf16 v[16:19], v[226:229], v[182:185], v[16:19]
	v_mfma_f32_16x16x32_bf16 v[4:7], v[218:221], v[206:209], v[4:7]
	v_mfma_f32_16x16x32_bf16 v[0:3], v[226:229], v[206:209], v[0:3]
	v_mfma_f32_16x16x32_bf16 v[52:55], v[222:225], v[170:173], v[52:55]
	v_mfma_f32_16x16x32_bf16 v[48:51], v[230:233], v[170:173], v[48:51]
	v_mfma_f32_16x16x32_bf16 v[36:39], v[222:225], v[178:181], v[36:39]
	v_mfma_f32_16x16x32_bf16 v[32:35], v[230:233], v[178:181], v[32:35]
	v_mfma_f32_16x16x32_bf16 v[20:23], v[222:225], v[186:189], v[20:23]
	v_mfma_f32_16x16x32_bf16 v[16:19], v[230:233], v[186:189], v[16:19]
	v_mfma_f32_16x16x32_bf16 v[4:7], v[222:225], v[214:217], v[4:7]
	v_mfma_f32_16x16x32_bf16 v[0:3], v[230:233], v[214:217], v[0:3]
	s_add_u32 s6, s6, 0x100
	s_addc_u32 s7, s7, 0
	s_cmp_ge_i32 s54, s49
	s_mov_b32 s2, s54
	s_barrier
	s_cbranch_scc1 .Lpost_272

.LBB0_325:
	s_add_i32 s83, s83, 1
	s_mul_i32 s6, s83, s18
	s_add_i32 s10, s6, s20
	s_cmpk_lt_i32 s10, 0x3b8
	s_cselect_b64 s[6:7], -1, 0
	s_cmpk_gt_i32 s10, 0x3b7
	s_cselect_b64 s[68:69], -1, 0
	s_and_b64 s[24:25], s[6:7], exec
	s_cselect_b32 s10, s10, 0
	s_ashr_i32 s21, s10, 31
	s_lshr_b32 s21, s21, 29
	s_add_i32 s21, s10, s21
	s_ashr_i32 s24, s21, 3
	s_and_b32 s21, s21, -8
	s_sub_i32 s10, s10, s21
	s_cmp_lt_i32 s10, 0
	s_movk_i32 s21, 0x78
	s_cselect_b32 s21, s21, 0x77
	s_mul_i32 s10, s21, s10
	s_add_i32 s21, s10, s24
	s_mul_hi_i32 s10, s21, 0x92492493
	s_add_i32 s10, s10, s21
	s_lshr_b32 s24, s10, 31
	s_ashr_i32 s10, s10, 4
	s_add_i32 s25, s10, s24
	s_lshl_b32 s37, s25, 2
	s_sub_i32 s10, 0x88, s37
	s_min_i32 s44, s10, 4
	s_abs_i32 s45, s44
	v_cvt_f32_u32_e32 v0, s45
	s_sub_i32 s46, 0, s45
	s_mul_i32 s25, s25, 28
	s_sub_i32 s21, s21, s25
	v_rcp_iflag_f32_e32 v0, v0
	s_mov_b32 s24, s36
	s_abs_i32 s36, s21
	s_xor_b32 s25, s21, s44
	v_mul_f32_e32 v0, 0x4f7ffffe, v0
	v_cvt_u32_f32_e32 v0, v0
	s_mov_b64 s[42:43], s[48:49]
	s_ashr_i32 s25, s25, 31
	s_mov_b32 s10, s66
	v_readfirstlane_b32 s47, v0
	s_mul_i32 s46, s46, s47
	s_mul_hi_u32 s46, s47, s46
	s_add_i32 s47, s47, s46
	s_mul_hi_u32 s46, s36, s47
	s_mul_i32 s47, s46, s45
	s_sub_i32 s36, s36, s47
	s_add_i32 s47, s46, 1
	s_sub_i32 s48, s36, s45
	s_cmp_ge_u32 s36, s45
	s_cselect_b32 s46, s47, s46
	s_cselect_b32 s36, s48, s36
	s_add_i32 s47, s46, 1
	s_cmp_ge_u32 s36, s45
	s_cselect_b32 s36, s47, s46
	s_xor_b32 s36, s36, s25
	s_sub_i32 s66, s36, s25
	s_mul_i32 s25, s66, s44
	s_sub_i32 s21, s21, s25
	s_add_i32 s36, s37, s21
	s_ashr_i32 s37, s36, 31
	s_lshl_b64 s[44:45], s[36:37], 19
	s_mov_b64 s[2:3], s[62:63]
	s_add_u32 s62, s58, s44
	s_addc_u32 s63, s59, s45
	s_and_b64 s[44:45], s[6:7], exec
	s_cselect_b32 s25, s63, s3
	s_cselect_b32 s37, s62, s2
	s_ashr_i32 s67, s66, 31
	s_lshl_b64 s[44:45], s[66:67], 19
	s_add_u32 s48, s19, s44
	s_addc_u32 s49, s34, s45
	s_and_b64 s[6:7], s[6:7], exec
	s_cselect_b32 s44, s49, s43
	s_cselect_b32 s45, s48, s42
	s_add_u32 s46, s42, 0x100
	s_addc_u32 s47, s43, 0
	s_add_u32 s6, s2, 0x40080
	s_addc_u32 s7, s3, 0
	s_mov_b32 s60, -2
	s_nop 0
	s_add_u32 s2, s6, 0xfffc0080
	s_addc_u32 s3, s7, -1
	s_add_i32 s21, 0, 0x10000
	v_add_u32_e32 v154, s21, v141
	ds_read_b128 v[136:139], v154
	ds_read_b128 v[150:153], v154 offset:1024
	ds_read_b128 v[162:165], v154 offset:2048
	ds_read_b128 v[166:169], v154 offset:3072
	s_cmp_eq_u32 s60, 12
	s_cselect_b32 s3, s25, s3
	s_cselect_b32 s2, s37, s2
	s_cselect_b32 s43, s44, s47
	s_cselect_b32 s42, s45, s46
	v_lshl_add_u64 v[154:155], s[6:7], 0, v[134:135]
	s_add_i32 m0, s53, 0xc000
	ds_read_b128 v[170:173], v149
	ds_read_b128 v[174:177], v149 offset:1024
	ds_read_b128 v[178:181], v149 offset:2048
	ds_read_b128 v[182:185], v149 offset:3072
	ds_read_b128 v[186:189], v149 offset:4096
	ds_read_b128 v[206:209], v149 offset:5120
	ds_read_b128 v[214:217], v149 offset:6144
	ds_read_b128 v[218:221], v149 offset:7168
	global_load_lds_dwordx4 v[154:155], off
	v_lshl_add_u64 v[154:155], s[6:7], 0, v[132:133]
	s_add_i32 m0, s53, 0xe000
	s_nop 0
	global_load_lds_dwordx4 v[154:155], off
	s_waitcnt lgkmcnt(8)
	s_barrier
	s_waitcnt lgkmcnt(0)
	v_mfma_f32_16x16x32_bf16 v[124:127], v[136:139], v[170:173], 0
	v_mfma_f32_16x16x32_bf16 v[120:123], v[162:165], v[170:173], 0
	v_mfma_f32_16x16x32_bf16 v[108:111], v[136:139], v[178:181], 0
	v_mfma_f32_16x16x32_bf16 v[104:107], v[162:165], v[178:181], 0
	v_mfma_f32_16x16x32_bf16 v[92:95], v[136:139], v[186:189], 0
	v_mfma_f32_16x16x32_bf16 v[88:91], v[162:165], v[186:189], 0
	v_mfma_f32_16x16x32_bf16 v[76:79], v[136:139], v[214:217], 0
	v_mfma_f32_16x16x32_bf16 v[72:75], v[162:165], v[214:217], 0
	v_mfma_f32_16x16x32_bf16 v[124:127], v[150:153], v[174:177], v[124:127]
	v_mfma_f32_16x16x32_bf16 v[120:123], v[166:169], v[174:177], v[120:123]
	v_mfma_f32_16x16x32_bf16 v[108:111], v[150:153], v[182:185], v[108:111]
	v_mfma_f32_16x16x32_bf16 v[104:107], v[166:169], v[182:185], v[104:107]
	v_mfma_f32_16x16x32_bf16 v[92:95], v[150:153], v[206:209], v[92:95]
	v_mfma_f32_16x16x32_bf16 v[88:91], v[166:169], v[206:209], v[88:91]
	v_mfma_f32_16x16x32_bf16 v[76:79], v[150:153], v[218:221], v[76:79]
	v_mfma_f32_16x16x32_bf16 v[72:75], v[166:169], v[218:221], v[72:75]
	s_barrier
	s_add_i32 s61, 0, 0x14000
	v_add_u32_e32 v154, s61, v141
	s_add_i32 s21, s21, s35
	ds_read_b128 v[222:225], v154
	ds_read_b128 v[226:229], v154 offset:1024
	ds_read_b128 v[230:233], v154 offset:2048
	ds_read_b128 v[234:237], v154 offset:3072
	v_lshl_add_u64 v[154:155], s[42:43], 0, v[130:131]
	s_mov_b32 m0, s21
	v_lshl_add_u64 v[238:239], s[42:43], 0, v[128:129]
	global_load_lds_dwordx4 v[154:155], off
	s_add_i32 m0, s21, 0x2000
	s_nop 0
	global_load_lds_dwordx4 v[238:239], off
	s_barrier
	s_waitcnt lgkmcnt(0)
	v_mfma_f32_16x16x32_bf16 v[116:119], v[222:225], v[170:173], 0
	v_mfma_f32_16x16x32_bf16 v[112:115], v[230:233], v[170:173], 0
	v_mfma_f32_16x16x32_bf16 v[100:103], v[222:225], v[178:181], 0
	v_mfma_f32_16x16x32_bf16 v[96:99], v[230:233], v[178:181], 0
	v_mfma_f32_16x16x32_bf16 v[84:87], v[222:225], v[186:189], 0
	v_mfma_f32_16x16x32_bf16 v[80:83], v[230:233], v[186:189], 0
	v_mfma_f32_16x16x32_bf16 v[68:71], v[222:225], v[214:217], 0
	v_mfma_f32_16x16x32_bf16 v[64:67], v[230:233], v[214:217], 0
	v_mfma_f32_16x16x32_bf16 v[116:119], v[226:229], v[174:177], v[116:119]
	v_mfma_f32_16x16x32_bf16 v[112:115], v[234:237], v[174:177], v[112:115]
	v_mfma_f32_16x16x32_bf16 v[100:103], v[226:229], v[182:185], v[100:103]
	v_mfma_f32_16x16x32_bf16 v[96:99], v[234:237], v[182:185], v[96:99]
	v_mfma_f32_16x16x32_bf16 v[84:87], v[226:229], v[206:209], v[84:87]
	v_mfma_f32_16x16x32_bf16 v[80:83], v[234:237], v[206:209], v[80:83]
	v_mfma_f32_16x16x32_bf16 v[68:71], v[226:229], v[218:221], v[68:71]
	v_mfma_f32_16x16x32_bf16 v[64:67], v[234:237], v[218:221], v[64:67]
	s_mov_b32 m0, s53
	v_lshl_add_u64 v[240:241], s[2:3], 0, v[130:131]
	s_barrier
	ds_read_b128 v[170:173], v149 offset:16384
	ds_read_b128 v[174:177], v149 offset:17408
	ds_read_b128 v[178:181], v149 offset:18432
	ds_read_b128 v[182:185], v149 offset:19456
	ds_read_b128 v[186:189], v149 offset:20480
	ds_read_b128 v[206:209], v149 offset:21504
	ds_read_b128 v[214:217], v149 offset:22528
	ds_read_b128 v[218:221], v149 offset:23552
	global_load_lds_dwordx4 v[240:241], off
	v_lshl_add_u64 v[242:243], s[2:3], 0, v[128:129]
	s_mov_b32 m0, s54
	s_nop 0
	global_load_lds_dwordx4 v[242:243], off
	s_barrier
	s_waitcnt lgkmcnt(0)
	v_mfma_f32_16x16x32_bf16 v[60:63], v[136:139], v[170:173], 0
	v_mfma_f32_16x16x32_bf16 v[56:59], v[162:165], v[170:173], 0
	v_mfma_f32_16x16x32_bf16 v[44:47], v[136:139], v[178:181], 0
	v_mfma_f32_16x16x32_bf16 v[40:43], v[162:165], v[178:181], 0
	v_mfma_f32_16x16x32_bf16 v[28:31], v[136:139], v[186:189], 0
	v_mfma_f32_16x16x32_bf16 v[24:27], v[162:165], v[186:189], 0
	v_mfma_f32_16x16x32_bf16 v[12:15], v[136:139], v[214:217], 0
	v_mfma_f32_16x16x32_bf16 v[8:11], v[162:165], v[214:217], 0
	v_mfma_f32_16x16x32_bf16 v[60:63], v[150:153], v[174:177], v[60:63]
	v_mfma_f32_16x16x32_bf16 v[56:59], v[166:169], v[174:177], v[56:59]
	v_mfma_f32_16x16x32_bf16 v[44:47], v[150:153], v[182:185], v[44:47]
	v_mfma_f32_16x16x32_bf16 v[40:43], v[166:169], v[182:185], v[40:43]
	v_mfma_f32_16x16x32_bf16 v[28:31], v[150:153], v[206:209], v[28:31]
	v_mfma_f32_16x16x32_bf16 v[24:27], v[166:169], v[206:209], v[24:27]
	v_mfma_f32_16x16x32_bf16 v[12:15], v[150:153], v[218:221], v[12:15]
	v_mfma_f32_16x16x32_bf16 v[8:11], v[166:169], v[218:221], v[8:11]
	s_barrier
	s_add_u32 s80, s42, 0x40000
	s_addc_u32 s81, s43, 0
	s_add_i32 s21, s61, s35
	v_lshl_add_u64 v[136:137], s[80:81], 0, v[130:131]
	s_mov_b32 m0, s21
	s_nop 0
	global_load_lds_dwordx4 v[136:137], off
	v_lshl_add_u64 v[136:137], s[80:81], 0, v[128:129]
	s_add_i32 m0, s21, 0x2000
	s_nop 0
	global_load_lds_dwordx4 v[136:137], off
	s_waitcnt vmcnt(6)
	s_barrier
	v_mfma_f32_16x16x32_bf16 v[52:55], v[222:225], v[170:173], 0
	v_mfma_f32_16x16x32_bf16 v[48:51], v[230:233], v[170:173], 0
	v_mfma_f32_16x16x32_bf16 v[36:39], v[222:225], v[178:181], 0
	v_mfma_f32_16x16x32_bf16 v[32:35], v[230:233], v[178:181], 0
	v_mfma_f32_16x16x32_bf16 v[20:23], v[222:225], v[186:189], 0
	v_mfma_f32_16x16x32_bf16 v[16:19], v[230:233], v[186:189], 0
	v_mfma_f32_16x16x32_bf16 v[4:7], v[222:225], v[214:217], 0
	v_mfma_f32_16x16x32_bf16 v[0:3], v[230:233], v[214:217], 0
	v_mfma_f32_16x16x32_bf16 v[52:55], v[226:229], v[174:177], v[52:55]
	v_mfma_f32_16x16x32_bf16 v[48:51], v[234:237], v[174:177], v[48:51]
	v_mfma_f32_16x16x32_bf16 v[36:39], v[226:229], v[182:185], v[36:39]
	v_mfma_f32_16x16x32_bf16 v[32:35], v[234:237], v[182:185], v[32:35]
	v_mfma_f32_16x16x32_bf16 v[20:23], v[226:229], v[206:209], v[20:23]
	v_mfma_f32_16x16x32_bf16 v[16:19], v[234:237], v[206:209], v[16:19]
	v_mfma_f32_16x16x32_bf16 v[4:7], v[226:229], v[218:221], v[4:7]
	v_mfma_f32_16x16x32_bf16 v[0:3], v[234:237], v[218:221], v[0:3]
	s_add_i32 s21, 0, 0x18000
	v_add_u32_e32 v156, s21, v141
	s_barrier
	ds_read_b128 v[136:139], v156
	ds_read_b128 v[150:153], v156 offset:1024
	ds_read_b128 v[162:165], v156 offset:2048
	ds_read_b128 v[166:169], v156 offset:3072
	s_add_u32 s2, s2, 0x40000
	s_addc_u32 s3, s3, 0
	s_mov_b32 m0, s55
	v_lshl_add_u64 v[222:223], s[2:3], 0, v[130:131]
	ds_read_b128 v[170:173], v149 offset:32768
	ds_read_b128 v[174:177], v149 offset:33792
	ds_read_b128 v[178:181], v149 offset:34816
	ds_read_b128 v[182:185], v149 offset:35840
	ds_read_b128 v[186:189], v149 offset:36864
	ds_read_b128 v[206:209], v149 offset:37888
	ds_read_b128 v[214:217], v149 offset:38912
	ds_read_b128 v[218:221], v149 offset:39936
	global_load_lds_dwordx4 v[222:223], off
	v_lshl_add_u64 v[222:223], s[2:3], 0, v[128:129]
	s_mov_b32 m0, s78
	s_nop 0
	global_load_lds_dwordx4 v[222:223], off
	s_waitcnt lgkmcnt(8)
	s_barrier
	s_waitcnt lgkmcnt(0)
	v_mfma_f32_16x16x32_bf16 v[124:127], v[136:139], v[170:173], v[124:127]
	v_mfma_f32_16x16x32_bf16 v[120:123], v[162:165], v[170:173], v[120:123]
	v_mfma_f32_16x16x32_bf16 v[108:111], v[136:139], v[178:181], v[108:111]
	v_mfma_f32_16x16x32_bf16 v[104:107], v[162:165], v[178:181], v[104:107]
	v_mfma_f32_16x16x32_bf16 v[92:95], v[136:139], v[186:189], v[92:95]
	v_mfma_f32_16x16x32_bf16 v[88:91], v[162:165], v[186:189], v[88:91]
	v_mfma_f32_16x16x32_bf16 v[76:79], v[136:139], v[214:217], v[76:79]
	v_mfma_f32_16x16x32_bf16 v[72:75], v[162:165], v[214:217], v[72:75]
	v_mfma_f32_16x16x32_bf16 v[124:127], v[150:153], v[174:177], v[124:127]
	v_mfma_f32_16x16x32_bf16 v[120:123], v[166:169], v[174:177], v[120:123]
	v_mfma_f32_16x16x32_bf16 v[108:111], v[150:153], v[182:185], v[108:111]
	v_mfma_f32_16x16x32_bf16 v[104:107], v[166:169], v[182:185], v[104:107]
	v_mfma_f32_16x16x32_bf16 v[92:95], v[150:153], v[206:209], v[92:95]
	v_mfma_f32_16x16x32_bf16 v[88:91], v[166:169], v[206:209], v[88:91]
	v_mfma_f32_16x16x32_bf16 v[76:79], v[150:153], v[218:221], v[76:79]
	v_mfma_f32_16x16x32_bf16 v[72:75], v[166:169], v[218:221], v[72:75]
	s_barrier
	s_add_i32 s61, 0, 0x1c000
	s_add_i32 s2, s21, s35
	v_add_u32_e32 v156, s61, v141
	v_lshl_add_u64 v[154:155], v[154:155], 0, s[50:51]
	s_mov_b32 m0, s2
	ds_read_b128 v[222:225], v156
	ds_read_b128 v[226:229], v156 offset:1024
	ds_read_b128 v[230:233], v156 offset:2048
	ds_read_b128 v[234:237], v156 offset:3072
	global_load_lds_dwordx4 v[154:155], off
	v_lshl_add_u64 v[154:155], v[238:239], 0, s[50:51]
	s_add_i32 m0, s2, 0x2000
	s_nop 0
	global_load_lds_dwordx4 v[154:155], off
	s_barrier
	s_waitcnt lgkmcnt(0)
	v_mfma_f32_16x16x32_bf16 v[116:119], v[222:225], v[170:173], v[116:119]
	v_mfma_f32_16x16x32_bf16 v[112:115], v[230:233], v[170:173], v[112:115]
	v_mfma_f32_16x16x32_bf16 v[100:103], v[222:225], v[178:181], v[100:103]
	v_mfma_f32_16x16x32_bf16 v[96:99], v[230:233], v[178:181], v[96:99]
	v_mfma_f32_16x16x32_bf16 v[84:87], v[222:225], v[186:189], v[84:87]
	v_mfma_f32_16x16x32_bf16 v[80:83], v[230:233], v[186:189], v[80:83]
	v_mfma_f32_16x16x32_bf16 v[68:71], v[222:225], v[214:217], v[68:71]
	v_mfma_f32_16x16x32_bf16 v[64:67], v[230:233], v[214:217], v[64:67]
	v_mfma_f32_16x16x32_bf16 v[116:119], v[226:229], v[174:177], v[116:119]
	v_mfma_f32_16x16x32_bf16 v[112:115], v[234:237], v[174:177], v[112:115]
	v_mfma_f32_16x16x32_bf16 v[100:103], v[226:229], v[182:185], v[100:103]
	v_mfma_f32_16x16x32_bf16 v[96:99], v[234:237], v[182:185], v[96:99]
	v_mfma_f32_16x16x32_bf16 v[84:87], v[226:229], v[206:209], v[84:87]
	v_mfma_f32_16x16x32_bf16 v[80:83], v[234:237], v[206:209], v[80:83]
	v_mfma_f32_16x16x32_bf16 v[68:71], v[226:229], v[218:221], v[68:71]
	v_mfma_f32_16x16x32_bf16 v[64:67], v[234:237], v[218:221], v[64:67]
	s_mov_b32 m0, s79
	v_lshl_add_u64 v[154:155], v[240:241], 0, s[50:51]
	s_barrier
	ds_read_b128 v[170:173], v149 offset:49152
	ds_read_b128 v[174:177], v149 offset:50176
	ds_read_b128 v[178:181], v149 offset:51200
	ds_read_b128 v[182:185], v149 offset:52224
	ds_read_b128 v[186:189], v149 offset:53248
	ds_read_b128 v[206:209], v149 offset:54272
	ds_read_b128 v[214:217], v149 offset:55296
	ds_read_b128 v[218:221], v149 offset:56320
	global_load_lds_dwordx4 v[154:155], off
	v_lshl_add_u64 v[154:155], v[242:243], 0, s[50:51]
	s_mov_b32 m0, s82
	s_nop 0
	global_load_lds_dwordx4 v[154:155], off
	s_barrier
	s_waitcnt lgkmcnt(0)
	v_mfma_f32_16x16x32_bf16 v[60:63], v[136:139], v[170:173], v[60:63]
	v_mfma_f32_16x16x32_bf16 v[56:59], v[162:165], v[170:173], v[56:59]
	v_mfma_f32_16x16x32_bf16 v[44:47], v[136:139], v[178:181], v[44:47]
	v_mfma_f32_16x16x32_bf16 v[40:43], v[162:165], v[178:181], v[40:43]
	v_mfma_f32_16x16x32_bf16 v[28:31], v[136:139], v[186:189], v[28:31]
	v_mfma_f32_16x16x32_bf16 v[24:27], v[162:165], v[186:189], v[24:27]
	v_mfma_f32_16x16x32_bf16 v[12:15], v[136:139], v[214:217], v[12:15]
	v_mfma_f32_16x16x32_bf16 v[8:11], v[162:165], v[214:217], v[8:11]
	v_mfma_f32_16x16x32_bf16 v[60:63], v[150:153], v[174:177], v[60:63]
	v_mfma_f32_16x16x32_bf16 v[56:59], v[166:169], v[174:177], v[56:59]
	v_mfma_f32_16x16x32_bf16 v[44:47], v[150:153], v[182:185], v[44:47]
	v_mfma_f32_16x16x32_bf16 v[40:43], v[166:169], v[182:185], v[40:43]
	v_mfma_f32_16x16x32_bf16 v[28:31], v[150:153], v[206:209], v[28:31]
	v_mfma_f32_16x16x32_bf16 v[24:27], v[166:169], v[206:209], v[24:27]
	v_mfma_f32_16x16x32_bf16 v[12:15], v[150:153], v[218:221], v[12:15]
	v_mfma_f32_16x16x32_bf16 v[8:11], v[166:169], v[218:221], v[8:11]
	s_barrier
	s_add_u32 s2, s42, 0x40080
	s_addc_u32 s3, s43, 0
	s_add_i32 s21, s61, s35
	v_lshl_add_u64 v[136:137], s[2:3], 0, v[130:131]
	s_mov_b32 m0, s21
	s_nop 0
	global_load_lds_dwordx4 v[136:137], off
	v_lshl_add_u64 v[136:137], s[2:3], 0, v[128:129]
	s_add_i32 m0, s21, 0x2000
	s_nop 0
	global_load_lds_dwordx4 v[136:137], off
	s_waitcnt vmcnt(6)
	s_barrier
	v_mfma_f32_16x16x32_bf16 v[52:55], v[222:225], v[170:173], v[52:55]
	v_mfma_f32_16x16x32_bf16 v[48:51], v[230:233], v[170:173], v[48:51]
	v_mfma_f32_16x16x32_bf16 v[36:39], v[222:225], v[178:181], v[36:39]
	v_mfma_f32_16x16x32_bf16 v[32:35], v[230:233], v[178:181], v[32:35]
	v_mfma_f32_16x16x32_bf16 v[20:23], v[222:225], v[186:189], v[20:23]
	v_mfma_f32_16x16x32_bf16 v[16:19], v[230:233], v[186:189], v[16:19]
	v_mfma_f32_16x16x32_bf16 v[4:7], v[222:225], v[214:217], v[4:7]
	v_mfma_f32_16x16x32_bf16 v[0:3], v[230:233], v[214:217], v[0:3]
	v_mfma_f32_16x16x32_bf16 v[52:55], v[226:229], v[174:177], v[52:55]
	v_mfma_f32_16x16x32_bf16 v[48:51], v[234:237], v[174:177], v[48:51]
	v_mfma_f32_16x16x32_bf16 v[36:39], v[226:229], v[182:185], v[36:39]
	v_mfma_f32_16x16x32_bf16 v[32:35], v[234:237], v[182:185], v[32:35]
	v_mfma_f32_16x16x32_bf16 v[20:23], v[226:229], v[206:209], v[20:23]
	v_mfma_f32_16x16x32_bf16 v[16:19], v[234:237], v[206:209], v[16:19]
	v_mfma_f32_16x16x32_bf16 v[4:7], v[226:229], v[218:221], v[4:7]
	v_mfma_f32_16x16x32_bf16 v[0:3], v[234:237], v[218:221], v[0:3]
	s_add_i32 s60, s60, 2
	s_add_u32 s46, s46, 0x100
	s_addc_u32 s47, s47, 0
	s_add_u32 s6, s6, 0x100
	s_addc_u32 s7, s7, 0
	s_cmp_gt_u32 s60, 13
	s_barrier
	s_cbranch_scc1 .Lpost_326

.LBB0_554:
	s_add_i32 s68, s68, 1
	s_mul_i32 s2, s68, s18
	s_add_i32 s10, s2, s20
	s_cmp_lt_i32 s10, s19
	s_cselect_b64 s[2:3], -1, 0
	s_cmp_ge_i32 s10, s19
	s_cselect_b64 s[38:39], -1, 0
	s_and_b64 s[6:7], s[2:3], exec
	s_cselect_b32 s6, s10, 0
	s_ashr_i32 s7, s6, 31
	s_lshr_b32 s7, s7, 29
	s_add_i32 s7, s6, s7
	s_ashr_i32 s10, s7, 3
	s_and_b32 s7, s7, -8
	s_sub_i32 s6, s6, s7
	s_cmp_lt_i32 s6, 0
	s_cselect_b32 s7, s61, s60
	s_mul_i32 s6, s7, s6
	s_add_i32 s10, s6, s10
	s_mul_hi_i32 s6, s10, 0x2e8ba2e9
	s_lshr_b32 s7, s6, 31
	s_ashr_i32 s6, s6, 4
	s_add_i32 s24, s6, s7
	s_lshl_b32 s25, s24, 2
	s_sub_i32 s6, s9, s25
	s_min_i32 s41, s6, 4
	s_abs_i32 s40, s41
	v_cvt_f32_u32_e32 v0, s40
	s_mov_b64 s[6:7], s[34:35]
	s_mov_b64 s[54:55], s[36:37]
	s_sub_i32 s35, 0, s40
	v_rcp_iflag_f32_e32 v0, v0
	s_mulk_i32 s24, 0x58
	s_sub_i32 s10, s10, s24
	s_abs_i32 s34, s10
	v_mul_f32_e32 v0, 0x4f7ffffe, v0
	v_cvt_u32_f32_e32 v0, v0
	s_xor_b32 s24, s10, s41
	s_ashr_i32 s24, s24, 31
	s_mov_b32 s73, -2
	v_readfirstlane_b32 s36, v0
	s_mul_i32 s35, s35, s36
	s_mul_hi_u32 s35, s36, s35
	s_add_i32 s36, s36, s35
	s_mul_hi_u32 s35, s34, s36
	s_mul_i32 s36, s35, s40
	s_sub_i32 s34, s34, s36
	s_add_i32 s36, s35, 1
	s_sub_i32 s37, s34, s40
	s_cmp_ge_u32 s34, s40
	s_cselect_b32 s35, s36, s35
	s_cselect_b32 s34, s37, s34
	s_add_i32 s36, s35, 1
	s_cmp_ge_u32 s34, s40
	s_cselect_b32 s34, s36, s35
	s_xor_b32 s34, s34, s24
	s_sub_i32 s40, s34, s24
	s_mul_i32 s24, s40, s41
	s_sub_i32 s10, s10, s24
	s_add_i32 s42, s25, s10
	s_ashr_i32 s43, s42, 31
	s_lshl_b64 s[24:25], s[42:43], 19
	s_add_u32 s34, s58, s24
	s_addc_u32 s35, s59, s25
	s_and_b64 s[24:25], s[2:3], exec
	s_cselect_b32 s10, s35, s7
	s_cselect_b32 s24, s34, s6
	s_ashr_i32 s41, s40, 31
	s_lshl_b64 s[36:37], s[40:41], 19
	s_add_u32 s36, s44, s36
	s_addc_u32 s37, s45, s37
	s_and_b64 s[2:3], s[2:3], exec
	s_cselect_b32 s25, s37, s55
	s_cselect_b32 s41, s36, s54
	s_add_u32 s43, s54, 0x100
	s_addc_u32 s69, s55, 0
	s_add_u32 s6, s6, 0x40080
	s_addc_u32 s7, s7, 0
	s_nop 0
	s_add_u32 s2, s6, 0xfffc0080
	s_addc_u32 s3, s7, -1
	s_add_i32 s77, 0, 0x10000
	v_add_u32_e32 v150, s77, v139
	ds_read_b128 v[134:137], v150
	ds_read_b128 v[142:145], v150 offset:1024
	ds_read_b128 v[146:149], v150 offset:2048
	ds_read_b128 v[150:153], v150 offset:3072
	s_cmp_eq_u32 s73, 12
	s_cselect_b32 s3, s10, s3
	s_cselect_b32 s2, s24, s2
	s_cselect_b32 s55, s25, s69
	s_cselect_b32 s54, s41, s43
	v_lshl_add_u64 v[154:155], s[6:7], 0, v[132:133]
	s_add_i32 m0, s47, 0xc000
	ds_read_b128 v[162:165], v141
	ds_read_b128 v[166:169], v141 offset:1024
	ds_read_b128 v[170:173], v141 offset:2048
	ds_read_b128 v[174:177], v141 offset:3072
	ds_read_b128 v[178:181], v141 offset:4096
	ds_read_b128 v[182:185], v141 offset:5120
	ds_read_b128 v[186:189], v141 offset:6144
	ds_read_b128 v[214:217], v141 offset:7168
	global_load_lds_dwordx4 v[154:155], off
	v_lshl_add_u64 v[154:155], s[6:7], 0, v[130:131]
	s_add_i32 m0, s47, 0xe000
	s_nop 0
	global_load_lds_dwordx4 v[154:155], off
	s_waitcnt lgkmcnt(8)
	s_barrier
	s_waitcnt lgkmcnt(0)
	v_mfma_f32_16x16x32_bf16 v[124:127], v[134:137], v[162:165], 0
	v_mfma_f32_16x16x32_bf16 v[116:119], v[146:149], v[162:165], 0
	v_mfma_f32_16x16x32_bf16 v[108:111], v[134:137], v[170:173], 0
	v_mfma_f32_16x16x32_bf16 v[100:103], v[146:149], v[170:173], 0
	v_mfma_f32_16x16x32_bf16 v[92:95], v[134:137], v[178:181], 0
	v_mfma_f32_16x16x32_bf16 v[84:87], v[146:149], v[178:181], 0
	v_mfma_f32_16x16x32_bf16 v[76:79], v[134:137], v[186:189], 0
	v_mfma_f32_16x16x32_bf16 v[68:71], v[146:149], v[186:189], 0
	v_mfma_f32_16x16x32_bf16 v[124:127], v[142:145], v[166:169], v[124:127]
	v_mfma_f32_16x16x32_bf16 v[116:119], v[150:153], v[166:169], v[116:119]
	v_mfma_f32_16x16x32_bf16 v[108:111], v[142:145], v[174:177], v[108:111]
	v_mfma_f32_16x16x32_bf16 v[100:103], v[150:153], v[174:177], v[100:103]
	v_mfma_f32_16x16x32_bf16 v[92:95], v[142:145], v[182:185], v[92:95]
	v_mfma_f32_16x16x32_bf16 v[84:87], v[150:153], v[182:185], v[84:87]
	v_mfma_f32_16x16x32_bf16 v[76:79], v[142:145], v[214:217], v[76:79]
	v_mfma_f32_16x16x32_bf16 v[68:71], v[150:153], v[214:217], v[68:71]
	s_barrier
	s_add_i32 s80, 0, 0x14000
	v_add_u32_e32 v154, s80, v139
	s_add_i32 s77, s77, s53
	ds_read_b128 v[218:221], v154
	ds_read_b128 v[222:225], v154 offset:1024
	ds_read_b128 v[226:229], v154 offset:2048
	ds_read_b128 v[230:233], v154 offset:3072
	v_lshl_add_u64 v[154:155], s[54:55], 0, v[156:157]
	s_mov_b32 m0, s77
	v_lshl_add_u64 v[206:207], s[54:55], 0, v[128:129]
	global_load_lds_dwordx4 v[154:155], off
	s_add_i32 m0, s77, 0x2000
	s_nop 0
	global_load_lds_dwordx4 v[206:207], off
	s_barrier
	s_waitcnt lgkmcnt(0)
	v_mfma_f32_16x16x32_bf16 v[120:123], v[218:221], v[162:165], 0
	v_mfma_f32_16x16x32_bf16 v[112:115], v[226:229], v[162:165], 0
	v_mfma_f32_16x16x32_bf16 v[104:107], v[218:221], v[170:173], 0
	v_mfma_f32_16x16x32_bf16 v[96:99], v[226:229], v[170:173], 0
	v_mfma_f32_16x16x32_bf16 v[88:91], v[218:221], v[178:181], 0
	v_mfma_f32_16x16x32_bf16 v[80:83], v[226:229], v[178:181], 0
	v_mfma_f32_16x16x32_bf16 v[72:75], v[218:221], v[186:189], 0
	v_mfma_f32_16x16x32_bf16 v[64:67], v[226:229], v[186:189], 0
	v_mfma_f32_16x16x32_bf16 v[120:123], v[222:225], v[166:169], v[120:123]
	v_mfma_f32_16x16x32_bf16 v[112:115], v[230:233], v[166:169], v[112:115]
	v_mfma_f32_16x16x32_bf16 v[104:107], v[222:225], v[174:177], v[104:107]
	v_mfma_f32_16x16x32_bf16 v[96:99], v[230:233], v[174:177], v[96:99]
	v_mfma_f32_16x16x32_bf16 v[88:91], v[222:225], v[182:185], v[88:91]
	v_mfma_f32_16x16x32_bf16 v[80:83], v[230:233], v[182:185], v[80:83]
	v_mfma_f32_16x16x32_bf16 v[72:75], v[222:225], v[214:217], v[72:75]
	v_mfma_f32_16x16x32_bf16 v[64:67], v[230:233], v[214:217], v[64:67]
	s_mov_b32 m0, s47
	v_lshl_add_u64 v[208:209], s[2:3], 0, v[156:157]
	s_barrier
	ds_read_b128 v[162:165], v141 offset:16384
	ds_read_b128 v[166:169], v141 offset:17408
	ds_read_b128 v[170:173], v141 offset:18432
	ds_read_b128 v[174:177], v141 offset:19456
	ds_read_b128 v[178:181], v141 offset:20480
	ds_read_b128 v[182:185], v141 offset:21504
	ds_read_b128 v[186:189], v141 offset:22528
	ds_read_b128 v[214:217], v141 offset:23552
	global_load_lds_dwordx4 v[208:209], off
	v_lshl_add_u64 v[234:235], s[2:3], 0, v[128:129]
	s_mov_b32 m0, s49
	s_nop 0
	global_load_lds_dwordx4 v[234:235], off
	s_barrier
	s_waitcnt lgkmcnt(0)
	v_mfma_f32_16x16x32_bf16 v[60:63], v[134:137], v[162:165], 0
	v_mfma_f32_16x16x32_bf16 v[52:55], v[146:149], v[162:165], 0
	v_mfma_f32_16x16x32_bf16 v[44:47], v[134:137], v[170:173], 0
	v_mfma_f32_16x16x32_bf16 v[36:39], v[146:149], v[170:173], 0
	v_mfma_f32_16x16x32_bf16 v[28:31], v[134:137], v[178:181], 0
	v_mfma_f32_16x16x32_bf16 v[20:23], v[146:149], v[178:181], 0
	v_mfma_f32_16x16x32_bf16 v[12:15], v[134:137], v[186:189], 0
	v_mfma_f32_16x16x32_bf16 v[4:7], v[146:149], v[186:189], 0
	v_mfma_f32_16x16x32_bf16 v[60:63], v[142:145], v[166:169], v[60:63]
	v_mfma_f32_16x16x32_bf16 v[52:55], v[150:153], v[166:169], v[52:55]
	v_mfma_f32_16x16x32_bf16 v[44:47], v[142:145], v[174:177], v[44:47]
	v_mfma_f32_16x16x32_bf16 v[36:39], v[150:153], v[174:177], v[36:39]
	v_mfma_f32_16x16x32_bf16 v[28:31], v[142:145], v[182:185], v[28:31]
	v_mfma_f32_16x16x32_bf16 v[20:23], v[150:153], v[182:185], v[20:23]
	v_mfma_f32_16x16x32_bf16 v[12:15], v[142:145], v[214:217], v[12:15]
	v_mfma_f32_16x16x32_bf16 v[4:7], v[150:153], v[214:217], v[4:7]
	s_barrier
	s_add_u32 s78, s54, 0x40000
	s_addc_u32 s79, s55, 0
	s_add_i32 s77, s80, s53
	v_lshl_add_u64 v[134:135], s[78:79], 0, v[156:157]
	s_mov_b32 m0, s77
	s_nop 0
	global_load_lds_dwordx4 v[134:135], off
	v_lshl_add_u64 v[134:135], s[78:79], 0, v[128:129]
	s_add_i32 m0, s77, 0x2000
	s_nop 0
	global_load_lds_dwordx4 v[134:135], off
	s_waitcnt vmcnt(6)
	s_barrier
	v_mfma_f32_16x16x32_bf16 v[56:59], v[218:221], v[162:165], 0
	v_mfma_f32_16x16x32_bf16 v[48:51], v[226:229], v[162:165], 0
	v_mfma_f32_16x16x32_bf16 v[40:43], v[218:221], v[170:173], 0
	v_mfma_f32_16x16x32_bf16 v[32:35], v[226:229], v[170:173], 0
	v_mfma_f32_16x16x32_bf16 v[24:27], v[218:221], v[178:181], 0
	v_mfma_f32_16x16x32_bf16 v[16:19], v[226:229], v[178:181], 0
	v_mfma_f32_16x16x32_bf16 v[8:11], v[218:221], v[186:189], 0
	v_mfma_f32_16x16x32_bf16 v[0:3], v[226:229], v[186:189], 0
	v_mfma_f32_16x16x32_bf16 v[56:59], v[222:225], v[166:169], v[56:59]
	v_mfma_f32_16x16x32_bf16 v[48:51], v[230:233], v[166:169], v[48:51]
	v_mfma_f32_16x16x32_bf16 v[40:43], v[222:225], v[174:177], v[40:43]
	v_mfma_f32_16x16x32_bf16 v[32:35], v[230:233], v[174:177], v[32:35]
	v_mfma_f32_16x16x32_bf16 v[24:27], v[222:225], v[182:185], v[24:27]
	v_mfma_f32_16x16x32_bf16 v[16:19], v[230:233], v[182:185], v[16:19]
	v_mfma_f32_16x16x32_bf16 v[8:11], v[222:225], v[214:217], v[8:11]
	v_mfma_f32_16x16x32_bf16 v[0:3], v[230:233], v[214:217], v[0:3]
	s_add_i32 s77, 0, 0x18000
	v_add_u32_e32 v150, s77, v139
	s_barrier
	ds_read_b128 v[134:137], v150
	ds_read_b128 v[142:145], v150 offset:1024
	ds_read_b128 v[146:149], v150 offset:2048
	ds_read_b128 v[150:153], v150 offset:3072
	s_add_u32 s2, s2, 0x40000
	s_addc_u32 s3, s3, 0
	s_mov_b32 m0, s62
	v_lshl_add_u64 v[218:219], s[2:3], 0, v[156:157]
	ds_read_b128 v[162:165], v141 offset:32768
	ds_read_b128 v[166:169], v141 offset:33792
	ds_read_b128 v[170:173], v141 offset:34816
	ds_read_b128 v[174:177], v141 offset:35840
	ds_read_b128 v[178:181], v141 offset:36864
	ds_read_b128 v[182:185], v141 offset:37888
	ds_read_b128 v[186:189], v141 offset:38912
	ds_read_b128 v[214:217], v141 offset:39936
	global_load_lds_dwordx4 v[218:219], off
	v_lshl_add_u64 v[218:219], s[2:3], 0, v[128:129]
	s_mov_b32 m0, s63
	s_nop 0
	global_load_lds_dwordx4 v[218:219], off
	s_waitcnt lgkmcnt(8)
	s_barrier
	s_waitcnt lgkmcnt(0)
	v_mfma_f32_16x16x32_bf16 v[124:127], v[134:137], v[162:165], v[124:127]
	v_mfma_f32_16x16x32_bf16 v[116:119], v[146:149], v[162:165], v[116:119]
	v_mfma_f32_16x16x32_bf16 v[108:111], v[134:137], v[170:173], v[108:111]
	v_mfma_f32_16x16x32_bf16 v[100:103], v[146:149], v[170:173], v[100:103]
	v_mfma_f32_16x16x32_bf16 v[92:95], v[134:137], v[178:181], v[92:95]
	v_mfma_f32_16x16x32_bf16 v[84:87], v[146:149], v[178:181], v[84:87]
	v_mfma_f32_16x16x32_bf16 v[76:79], v[134:137], v[186:189], v[76:79]
	v_mfma_f32_16x16x32_bf16 v[68:71], v[146:149], v[186:189], v[68:71]
	v_mfma_f32_16x16x32_bf16 v[124:127], v[142:145], v[166:169], v[124:127]
	v_mfma_f32_16x16x32_bf16 v[116:119], v[150:153], v[166:169], v[116:119]
	v_mfma_f32_16x16x32_bf16 v[108:111], v[142:145], v[174:177], v[108:111]
	v_mfma_f32_16x16x32_bf16 v[100:103], v[150:153], v[174:177], v[100:103]
	v_mfma_f32_16x16x32_bf16 v[92:95], v[142:145], v[182:185], v[92:95]
	v_mfma_f32_16x16x32_bf16 v[84:87], v[150:153], v[182:185], v[84:87]
	v_mfma_f32_16x16x32_bf16 v[76:79], v[142:145], v[214:217], v[76:79]
	v_mfma_f32_16x16x32_bf16 v[68:71], v[150:153], v[214:217], v[68:71]
	s_barrier
	s_add_i32 s78, 0, 0x1c000
	s_add_i32 s2, s77, s53
	v_add_u32_e32 v161, s78, v139
	v_lshl_add_u64 v[154:155], v[154:155], 0, s[50:51]
	s_mov_b32 m0, s2
	ds_read_b128 v[218:221], v161
	ds_read_b128 v[222:225], v161 offset:1024
	ds_read_b128 v[226:229], v161 offset:2048
	ds_read_b128 v[230:233], v161 offset:3072
	global_load_lds_dwordx4 v[154:155], off
	v_lshl_add_u64 v[154:155], v[206:207], 0, s[50:51]
	s_add_i32 m0, s2, 0x2000
	s_nop 0
	global_load_lds_dwordx4 v[154:155], off
	s_barrier
	s_waitcnt lgkmcnt(0)
	v_mfma_f32_16x16x32_bf16 v[120:123], v[218:221], v[162:165], v[120:123]
	v_mfma_f32_16x16x32_bf16 v[112:115], v[226:229], v[162:165], v[112:115]
	v_mfma_f32_16x16x32_bf16 v[104:107], v[218:221], v[170:173], v[104:107]
	v_mfma_f32_16x16x32_bf16 v[96:99], v[226:229], v[170:173], v[96:99]
	v_mfma_f32_16x16x32_bf16 v[88:91], v[218:221], v[178:181], v[88:91]
	v_mfma_f32_16x16x32_bf16 v[80:83], v[226:229], v[178:181], v[80:83]
	v_mfma_f32_16x16x32_bf16 v[72:75], v[218:221], v[186:189], v[72:75]
	v_mfma_f32_16x16x32_bf16 v[64:67], v[226:229], v[186:189], v[64:67]
	v_mfma_f32_16x16x32_bf16 v[120:123], v[222:225], v[166:169], v[120:123]
	v_mfma_f32_16x16x32_bf16 v[112:115], v[230:233], v[166:169], v[112:115]
	v_mfma_f32_16x16x32_bf16 v[104:107], v[222:225], v[174:177], v[104:107]
	v_mfma_f32_16x16x32_bf16 v[96:99], v[230:233], v[174:177], v[96:99]
	v_mfma_f32_16x16x32_bf16 v[88:91], v[222:225], v[182:185], v[88:91]
	v_mfma_f32_16x16x32_bf16 v[80:83], v[230:233], v[182:185], v[80:83]
	v_mfma_f32_16x16x32_bf16 v[72:75], v[222:225], v[214:217], v[72:75]
	v_mfma_f32_16x16x32_bf16 v[64:67], v[230:233], v[214:217], v[64:67]
	s_mov_b32 m0, s66
	v_lshl_add_u64 v[154:155], v[208:209], 0, s[50:51]
	s_barrier
	ds_read_b128 v[162:165], v141 offset:49152
	ds_read_b128 v[166:169], v141 offset:50176
	ds_read_b128 v[170:173], v141 offset:51200
	ds_read_b128 v[174:177], v141 offset:52224
	ds_read_b128 v[178:181], v141 offset:53248
	ds_read_b128 v[182:185], v141 offset:54272
	ds_read_b128 v[186:189], v141 offset:55296
	ds_read_b128 v[214:217], v141 offset:56320
	global_load_lds_dwordx4 v[154:155], off
	v_lshl_add_u64 v[154:155], v[234:235], 0, s[50:51]
	s_mov_b32 m0, s67
	s_nop 0
	global_load_lds_dwordx4 v[154:155], off
	s_barrier
	s_waitcnt lgkmcnt(0)
	v_mfma_f32_16x16x32_bf16 v[60:63], v[134:137], v[162:165], v[60:63]
	v_mfma_f32_16x16x32_bf16 v[52:55], v[146:149], v[162:165], v[52:55]
	v_mfma_f32_16x16x32_bf16 v[44:47], v[134:137], v[170:173], v[44:47]
	v_mfma_f32_16x16x32_bf16 v[36:39], v[146:149], v[170:173], v[36:39]
	v_mfma_f32_16x16x32_bf16 v[28:31], v[134:137], v[178:181], v[28:31]
	v_mfma_f32_16x16x32_bf16 v[20:23], v[146:149], v[178:181], v[20:23]
	v_mfma_f32_16x16x32_bf16 v[12:15], v[134:137], v[186:189], v[12:15]
	v_mfma_f32_16x16x32_bf16 v[4:7], v[146:149], v[186:189], v[4:7]
	v_mfma_f32_16x16x32_bf16 v[60:63], v[142:145], v[166:169], v[60:63]
	v_mfma_f32_16x16x32_bf16 v[52:55], v[150:153], v[166:169], v[52:55]
	v_mfma_f32_16x16x32_bf16 v[44:47], v[142:145], v[174:177], v[44:47]
	v_mfma_f32_16x16x32_bf16 v[36:39], v[150:153], v[174:177], v[36:39]
	v_mfma_f32_16x16x32_bf16 v[28:31], v[142:145], v[182:185], v[28:31]
	v_mfma_f32_16x16x32_bf16 v[20:23], v[150:153], v[182:185], v[20:23]
	v_mfma_f32_16x16x32_bf16 v[12:15], v[142:145], v[214:217], v[12:15]
	v_mfma_f32_16x16x32_bf16 v[4:7], v[150:153], v[214:217], v[4:7]
	s_barrier
	s_add_u32 s2, s54, 0x40080
	s_addc_u32 s3, s55, 0
	s_add_i32 s54, s78, s53
	v_lshl_add_u64 v[134:135], s[2:3], 0, v[156:157]
	s_mov_b32 m0, s54
	s_nop 0
	global_load_lds_dwordx4 v[134:135], off
	v_lshl_add_u64 v[134:135], s[2:3], 0, v[128:129]
	s_add_i32 m0, s54, 0x2000
	s_nop 0
	global_load_lds_dwordx4 v[134:135], off
	s_waitcnt vmcnt(6)
	s_barrier
	v_mfma_f32_16x16x32_bf16 v[56:59], v[218:221], v[162:165], v[56:59]
	v_mfma_f32_16x16x32_bf16 v[48:51], v[226:229], v[162:165], v[48:51]
	v_mfma_f32_16x16x32_bf16 v[40:43], v[218:221], v[170:173], v[40:43]
	v_mfma_f32_16x16x32_bf16 v[32:35], v[226:229], v[170:173], v[32:35]
	v_mfma_f32_16x16x32_bf16 v[24:27], v[218:221], v[178:181], v[24:27]
	v_mfma_f32_16x16x32_bf16 v[16:19], v[226:229], v[178:181], v[16:19]
	v_mfma_f32_16x16x32_bf16 v[8:11], v[218:221], v[186:189], v[8:11]
	v_mfma_f32_16x16x32_bf16 v[0:3], v[226:229], v[186:189], v[0:3]
	v_mfma_f32_16x16x32_bf16 v[56:59], v[222:225], v[166:169], v[56:59]
	v_mfma_f32_16x16x32_bf16 v[48:51], v[230:233], v[166:169], v[48:51]
	v_mfma_f32_16x16x32_bf16 v[40:43], v[222:225], v[174:177], v[40:43]
	v_mfma_f32_16x16x32_bf16 v[32:35], v[230:233], v[174:177], v[32:35]
	v_mfma_f32_16x16x32_bf16 v[24:27], v[222:225], v[182:185], v[24:27]
	v_mfma_f32_16x16x32_bf16 v[16:19], v[230:233], v[182:185], v[16:19]
	v_mfma_f32_16x16x32_bf16 v[8:11], v[222:225], v[214:217], v[8:11]
	v_mfma_f32_16x16x32_bf16 v[0:3], v[230:233], v[214:217], v[0:3]
	s_add_i32 s73, s73, 2
	s_add_u32 s43, s43, 0x100
	s_addc_u32 s69, s69, 0
	s_add_u32 s6, s6, 0x100
	s_addc_u32 s7, s7, 0
	s_cmp_gt_u32 s73, 13
	s_barrier
	s_cbranch_scc1 .Lpost_555
